# v30 + GEMM K-loops (in-proj, out-proj, up, down) issue tile DMA loads as SGPR base + 32-bit VGPR offset, removing 16 64-bit VALU adds per 2 K-tiles
# speedup vs baseline: 1.0111x; 1.0022x over previous
; #define PG8_STAGE(bufoff, gbase, voff) do { _Pragma("unroll") for (int _i = 0; _i < 2; ++_i) \
;         __builtin_amdgcn_global_load_lds((const unsigned*)((const char*)(gbase) + (voff)[_i]), (PG8_LAS unsigned*)(lds + (bufoff) + ldsw + _i * 8192), 16, 0, 0); } while (0)
; #define PG8_LDA(dst, b, h) do { _Pragma("unroll") for (int m = 0; m < 4; ++m) _Pragma("unroll") for (int k = 0; k < 2; ++k) dst[m][k] = *(const PG8_LAS bf16x8*)(lds + PG8_SA(b, h) + aoff + m * 2048 + k * 1024); } while (0)
; #define PG8_LDB(dst, b, h) do { _Pragma("unroll") for (int n = 0; n < 2; ++n) _Pragma("unroll") for (int k = 0; k < 2; ++k) dst[n][k] = *(const PG8_LAS bf16x8*)(lds + PG8_SB(b, h) + boff + n * 2048 + k * 1024); } while (0)
; #define PG8_MMA(ai, bj, At, Bt) do { __builtin_amdgcn_s_setprio(1); _Pragma("unroll") for (int m = 0; m < 4; ++m) _Pragma("unroll") for (int n = 0; n < 2; ++n) _Pragma("unroll") for (int k = 0; k < 2; ++k) \
;         acc[ai][bj][m][n] = __builtin_amdgcn_mfma_f32_16x16x32_bf16(Bt[n][k], At[m][k], acc[ai][bj][m][n], 0, 0, 0); __builtin_amdgcn_s_setprio(0); } while (0)
; #define PG8_WAIT_V(n) asm volatile("s_waitcnt vmcnt(" #n ")" ::: "memory")
; #define PG8_WAIT_L(n) asm volatile("s_waitcnt lgkmcnt(" #n ")" ::: "memory")
; #define PG8_BAR __builtin_amdgcn_s_barrier()
; #define PG8_SCHED __builtin_amdgcn_sched_barrier(0)
; template <class Epi, class Sched, bool ALIGN_EPI = false, bool SP2 = false>
; __device__ __forceinline__ void gemm_phase(PG8_LAS unsigned char* lds, const Gemm g, const Sched& S, const Epi& E, int wv) {
;     ...
;             PG8_LDB(B0, 0, 0); PG8_LDB(B1, 0, 1); PG8_SCHED; PG8_LDA(At, 0, 0); PG8_STAGE(PG8_SA(1, 1), a1 + hstepA, voffA);
;             PG8_WAIT_V(8); PG8_WAIT_L(0); PG8_BAR; PG8_MMA(0, 0, At, B0); PG8_MMA(0, 1, At, B1); PG8_BAR; PG8_SCHED;
;             PG8_LDA(At, 0, 1); PG8_STAGE(PG8_SB(0, 0), b2, voffB); PG8_STAGE(PG8_SB(0, 1), b2 + hstepB, voffB); PG8_STAGE(PG8_SA(0, 0), a2, voffA);
;             PG8_WAIT_V(8); PG8_WAIT_L(0); PG8_BAR; PG8_MMA(1, 0, At, B0); PG8_MMA(1, 1, At, B1); PG8_BAR; PG8_SCHED;
.LBB0_1645:
	s_waitcnt lgkmcnt(0)
	ds_read_b128 v[154:157], v182
	ds_read_b128 v[158:161], v182 offset:1024
	ds_read_b128 v[162:165], v182 offset:2048
	ds_read_b128 v[166:169], v182 offset:3072
	ds_read_b128 v[170:173], v183
	ds_read_b128 v[174:177], v183 offset:1024
	ds_read_b128 v[188:191], v183 offset:2048
	ds_read_b128 v[192:195], v183 offset:3072
	s_add_u32 s2, s8, 0xfffc0080
	s_addc_u32 s3, s9, -1
	s_cmp_eq_u32 vcc_lo, 12
	s_cselect_b32 s79, s7, s3
	s_cselect_b32 s78, s67, s2
	s_cselect_b32 s77, s69, s97
	s_cselect_b32 s76, s71, s96
	s_add_i32 m0, s83, 0xc000
	ds_read_b128 v[196:199], v184
	ds_read_b128 v[200:203], v184 offset:1024
	ds_read_b128 v[204:207], v184 offset:2048
	ds_read_b128 v[208:211], v184 offset:3072
	ds_read_b128 v[212:215], v184 offset:4096
	ds_read_b128 v[216:219], v184 offset:5120
	ds_read_b128 v[220:223], v184 offset:6144
	ds_read_b128 v[224:227], v184 offset:7168
	global_load_lds_dwordx4 v146, s[8:9]
	s_add_i32 m0, s83, 0xe000
	s_nop 0
	global_load_lds_dwordx4 v148, s[8:9]
	s_waitcnt vmcnt(8)
	s_waitcnt lgkmcnt(0)
	s_barrier
	s_setprio 1
	s_waitcnt lgkmcnt(0)
	v_mfma_f32_16x16x32_bf16 v[124:127], v[154:157], v[196:199], v[124:127]
	v_mfma_f32_16x16x32_bf16 v[120:123], v[162:165], v[196:199], v[120:123]
	v_mfma_f32_16x16x32_bf16 v[108:111], v[154:157], v[204:207], v[108:111]
	v_mfma_f32_16x16x32_bf16 v[104:107], v[162:165], v[204:207], v[104:107]
	v_mfma_f32_16x16x32_bf16 v[92:95], v[154:157], v[212:215], v[92:95]
	v_mfma_f32_16x16x32_bf16 v[88:91], v[162:165], v[212:215], v[88:91]
	v_mfma_f32_16x16x32_bf16 v[76:79], v[154:157], v[220:223], v[76:79]
	v_mfma_f32_16x16x32_bf16 v[72:75], v[162:165], v[220:223], v[72:75]
	v_mfma_f32_16x16x32_bf16 v[124:127], v[158:161], v[200:203], v[124:127]
	v_mfma_f32_16x16x32_bf16 v[120:123], v[166:169], v[200:203], v[120:123]
	v_mfma_f32_16x16x32_bf16 v[108:111], v[158:161], v[208:211], v[108:111]
	v_mfma_f32_16x16x32_bf16 v[104:107], v[166:169], v[208:211], v[104:107]
	v_mfma_f32_16x16x32_bf16 v[92:95], v[158:161], v[216:219], v[92:95]
	v_mfma_f32_16x16x32_bf16 v[88:91], v[166:169], v[216:219], v[88:91]
	v_mfma_f32_16x16x32_bf16 v[76:79], v[158:161], v[224:227], v[76:79]
	v_mfma_f32_16x16x32_bf16 v[72:75], v[166:169], v[224:227], v[72:75]
	s_setprio 0
	s_setprio 1
	v_mfma_f32_16x16x32_bf16 v[116:119], v[170:173], v[196:199], v[116:119]
	v_mfma_f32_16x16x32_bf16 v[112:115], v[188:191], v[196:199], v[112:115]
	v_mfma_f32_16x16x32_bf16 v[100:103], v[170:173], v[204:207], v[100:103]
	v_mfma_f32_16x16x32_bf16 v[96:99], v[188:191], v[204:207], v[96:99]
	v_mfma_f32_16x16x32_bf16 v[84:87], v[170:173], v[212:215], v[84:87]
	v_mfma_f32_16x16x32_bf16 v[80:83], v[188:191], v[212:215], v[80:83]
	v_mfma_f32_16x16x32_bf16 v[68:71], v[170:173], v[220:223], v[68:71]
	v_mfma_f32_16x16x32_bf16 v[64:67], v[188:191], v[220:223], v[64:67]
	v_mfma_f32_16x16x32_bf16 v[116:119], v[174:177], v[200:203], v[116:119]
	v_mfma_f32_16x16x32_bf16 v[112:115], v[192:195], v[200:203], v[112:115]
	v_mfma_f32_16x16x32_bf16 v[100:103], v[174:177], v[208:211], v[100:103]
	v_mfma_f32_16x16x32_bf16 v[96:99], v[192:195], v[208:211], v[96:99]
	v_mfma_f32_16x16x32_bf16 v[84:87], v[174:177], v[216:219], v[84:87]
	v_mfma_f32_16x16x32_bf16 v[80:83], v[192:195], v[216:219], v[80:83]
	v_mfma_f32_16x16x32_bf16 v[68:71], v[174:177], v[224:227], v[68:71]
	v_mfma_f32_16x16x32_bf16 v[64:67], v[192:195], v[224:227], v[64:67]
	s_setprio 0
	s_barrier
	s_add_i32 s2, s91, s82
	s_mov_b32 m0, s2
	ds_read_b128 v[196:199], v184 offset:16384
	ds_read_b128 v[200:203], v184 offset:17408
	ds_read_b128 v[204:207], v184 offset:18432
	ds_read_b128 v[208:211], v184 offset:19456
	ds_read_b128 v[212:215], v184 offset:20480
	ds_read_b128 v[216:219], v184 offset:21504
	ds_read_b128 v[220:223], v184 offset:22528
	ds_read_b128 v[224:227], v184 offset:23552
	global_load_lds_dwordx4 v130, s[76:77]
	s_add_i32 m0, s2, 0x2000
	s_add_u32 s2, s76, 0x40000
	s_addc_u32 s3, s77, 0
	s_add_i32 vcc_hi, s92, s82
	global_load_lds_dwordx4 v134, s[76:77]
	s_mov_b32 m0, vcc_hi
	s_nop 0
	global_load_lds_dwordx4 v130, s[2:3]
	s_add_i32 m0, vcc_hi, 0x2000
	s_nop 0
	global_load_lds_dwordx4 v134, s[2:3]
	s_mov_b32 m0, s83
	s_nop 0
	global_load_lds_dwordx4 v128, s[78:79]
	s_mov_b32 m0, s84
	s_nop 0
	global_load_lds_dwordx4 v132, s[78:79]
	s_waitcnt vmcnt(8)
	s_waitcnt lgkmcnt(0)
	s_barrier
	s_setprio 1
	s_waitcnt lgkmcnt(0)
	v_mfma_f32_16x16x32_bf16 v[60:63], v[154:157], v[196:199], v[60:63]
	v_mfma_f32_16x16x32_bf16 v[56:59], v[162:165], v[196:199], v[56:59]
	v_mfma_f32_16x16x32_bf16 v[44:47], v[154:157], v[204:207], v[44:47]
	v_mfma_f32_16x16x32_bf16 v[40:43], v[162:165], v[204:207], v[40:43]
	v_mfma_f32_16x16x32_bf16 v[28:31], v[154:157], v[212:215], v[28:31]
	v_mfma_f32_16x16x32_bf16 v[24:27], v[162:165], v[212:215], v[24:27]
	v_mfma_f32_16x16x32_bf16 v[12:15], v[154:157], v[220:223], v[12:15]
	v_mfma_f32_16x16x32_bf16 v[8:11], v[162:165], v[220:223], v[8:11]
	v_mfma_f32_16x16x32_bf16 v[60:63], v[158:161], v[200:203], v[60:63]
	v_mfma_f32_16x16x32_bf16 v[56:59], v[166:169], v[200:203], v[56:59]
	v_mfma_f32_16x16x32_bf16 v[44:47], v[158:161], v[208:211], v[44:47]
	v_mfma_f32_16x16x32_bf16 v[40:43], v[166:169], v[208:211], v[40:43]
	v_mfma_f32_16x16x32_bf16 v[28:31], v[158:161], v[216:219], v[28:31]
	v_mfma_f32_16x16x32_bf16 v[24:27], v[166:169], v[216:219], v[24:27]
	v_mfma_f32_16x16x32_bf16 v[12:15], v[158:161], v[224:227], v[12:15]
	v_mfma_f32_16x16x32_bf16 v[8:11], v[166:169], v[224:227], v[8:11]
	s_setprio 0
	s_setprio 1
	v_mfma_f32_16x16x32_bf16 v[52:55], v[170:173], v[196:199], v[52:55]
	v_mfma_f32_16x16x32_bf16 v[48:51], v[188:191], v[196:199], v[48:51]
	v_mfma_f32_16x16x32_bf16 v[36:39], v[170:173], v[204:207], v[36:39]
	v_mfma_f32_16x16x32_bf16 v[32:35], v[188:191], v[204:207], v[32:35]
	v_mfma_f32_16x16x32_bf16 v[20:23], v[170:173], v[212:215], v[20:23]
	v_mfma_f32_16x16x32_bf16 v[16:19], v[188:191], v[212:215], v[16:19]
	v_mfma_f32_16x16x32_bf16 v[4:7], v[170:173], v[220:223], v[4:7]
	v_mfma_f32_16x16x32_bf16 v[0:3], v[188:191], v[220:223], v[0:3]
	v_mfma_f32_16x16x32_bf16 v[52:55], v[174:177], v[200:203], v[52:55]
	v_mfma_f32_16x16x32_bf16 v[48:51], v[192:195], v[200:203], v[48:51]
	v_mfma_f32_16x16x32_bf16 v[36:39], v[174:177], v[208:211], v[36:39]
	v_mfma_f32_16x16x32_bf16 v[32:35], v[192:195], v[208:211], v[32:35]
	v_mfma_f32_16x16x32_bf16 v[20:23], v[174:177], v[216:219], v[20:23]
	v_mfma_f32_16x16x32_bf16 v[16:19], v[192:195], v[216:219], v[16:19]
	v_mfma_f32_16x16x32_bf16 v[4:7], v[174:177], v[224:227], v[4:7]
	v_mfma_f32_16x16x32_bf16 v[0:3], v[192:195], v[224:227], v[0:3]
	s_setprio 0
	s_barrier
; #define PG8_STAGE(bufoff, gbase, voff) do { _Pragma("unroll") for (int _i = 0; _i < 2; ++_i) \
;         __builtin_amdgcn_global_load_lds((const unsigned*)((const char*)(gbase) + (voff)[_i]), (PG8_LAS unsigned*)(lds + (bufoff) + ldsw + _i * 8192), 16, 0, 0); } while (0)
; #define PG8_LDA(dst, b, h) do { _Pragma("unroll") for (int m = 0; m < 4; ++m) _Pragma("unroll") for (int k = 0; k < 2; ++k) dst[m][k] = *(const PG8_LAS bf16x8*)(lds + PG8_SA(b, h) + aoff + m * 2048 + k * 1024); } while (0)
; #define PG8_LDB(dst, b, h) do { _Pragma("unroll") for (int n = 0; n < 2; ++n) _Pragma("unroll") for (int k = 0; k < 2; ++k) dst[n][k] = *(const PG8_LAS bf16x8*)(lds + PG8_SB(b, h) + boff + n * 2048 + k * 1024); } while (0)
; #define PG8_MMA(ai, bj, At, Bt) do { __builtin_amdgcn_s_setprio(1); _Pragma("unroll") for (int m = 0; m < 4; ++m) _Pragma("unroll") for (int n = 0; n < 2; ++n) _Pragma("unroll") for (int k = 0; k < 2; ++k) \
;         acc[ai][bj][m][n] = __builtin_amdgcn_mfma_f32_16x16x32_bf16(Bt[n][k], At[m][k], acc[ai][bj][m][n], 0, 0, 0); __builtin_amdgcn_s_setprio(0); } while (0)
; #define PG8_WAIT_V(n) asm volatile("s_waitcnt vmcnt(" #n ")" ::: "memory")
; #define PG8_WAIT_L(n) asm volatile("s_waitcnt lgkmcnt(" #n ")" ::: "memory")
; #define PG8_BAR __builtin_amdgcn_s_barrier()
; template <class Epi, class Sched, bool ALIGN_EPI = false, bool SP2 = false>
; __device__ __forceinline__ void gemm_phase(PG8_LAS unsigned char* lds, const Gemm g, const Sched& S, const Epi& E, int wv) {
;     ...
;         for (int t = 0; t < nt; t += 2) {
;             const bool last = (t == nt - 2);
;             const char* a1 = cA + (size_t)(t + 1) * kstep;
;             const char* a2 = last ? nA : cA + (size_t)(t + 2) * kstep; const char* b2 = last ? nB : cB + (size_t)(t + 2) * kstep;
;             const char* a3 = a2 + kstep; const char* b3 = b2 + kstep;
;     ...
;             PG8_LDB(B0, 1, 0); PG8_LDB(B1, 1, 1); PG8_SCHED; PG8_LDA(At, 1, 0); PG8_STAGE(PG8_SA(0, 1), a2 + hstepA, voffA);
;             PG8_WAIT_V(8); PG8_WAIT_L(0); PG8_BAR; PG8_MMA(0, 0, At, B0); PG8_MMA(0, 1, At, B1); PG8_BAR; PG8_SCHED;
;             PG8_LDA(At, 1, 1); PG8_STAGE(PG8_SB(1, 0), b3, voffB); PG8_STAGE(PG8_SB(1, 1), b3 + hstepB, voffB); PG8_STAGE(PG8_SA(1, 0), a3, voffA);
;             PG8_WAIT_V(8); PG8_WAIT_L(0); PG8_BAR; PG8_MMA(1, 0, At, B0); PG8_MMA(1, 1, At, B1); PG8_BAR; PG8_SCHED;
	s_add_i32 vcc_hi, 0, 0x18000
	v_add_u32_e32 v136, vcc_hi, v178
	s_add_i32 s42, 0, 0x1c000
	ds_read_b128 v[154:157], v136
	ds_read_b128 v[158:161], v136 offset:1024
	ds_read_b128 v[162:165], v136 offset:2048
	ds_read_b128 v[166:169], v136 offset:3072
	v_add_u32_e32 v136, s42, v178
	ds_read_b128 v[170:173], v136
	ds_read_b128 v[174:177], v136 offset:1024
	ds_read_b128 v[188:191], v136 offset:2048
	ds_read_b128 v[192:195], v136 offset:3072
	s_add_u32 s2, s78, 0x40000
	s_addc_u32 s3, s79, 0
	s_mov_b32 m0, s85
	ds_read_b128 v[196:199], v184 offset:32768
	ds_read_b128 v[200:203], v184 offset:33792
	ds_read_b128 v[204:207], v184 offset:34816
	ds_read_b128 v[208:211], v184 offset:35840
	ds_read_b128 v[212:215], v184 offset:36864
	ds_read_b128 v[216:219], v184 offset:37888
	ds_read_b128 v[220:223], v184 offset:38912
	ds_read_b128 v[224:227], v184 offset:39936
	global_load_lds_dwordx4 v128, s[2:3]
	s_mov_b32 m0, s86
	s_nop 0
	global_load_lds_dwordx4 v132, s[2:3]
	s_waitcnt vmcnt(8)
	s_waitcnt lgkmcnt(0)
	s_barrier
	s_setprio 1
	s_waitcnt lgkmcnt(0)
	v_mfma_f32_16x16x32_bf16 v[124:127], v[154:157], v[196:199], v[124:127]
	v_mfma_f32_16x16x32_bf16 v[120:123], v[162:165], v[196:199], v[120:123]
	v_mfma_f32_16x16x32_bf16 v[108:111], v[154:157], v[204:207], v[108:111]
	v_mfma_f32_16x16x32_bf16 v[104:107], v[162:165], v[204:207], v[104:107]
	v_mfma_f32_16x16x32_bf16 v[92:95], v[154:157], v[212:215], v[92:95]
	v_mfma_f32_16x16x32_bf16 v[88:91], v[162:165], v[212:215], v[88:91]
	v_mfma_f32_16x16x32_bf16 v[76:79], v[154:157], v[220:223], v[76:79]
	v_mfma_f32_16x16x32_bf16 v[72:75], v[162:165], v[220:223], v[72:75]
	v_mfma_f32_16x16x32_bf16 v[124:127], v[158:161], v[200:203], v[124:127]
	v_mfma_f32_16x16x32_bf16 v[120:123], v[166:169], v[200:203], v[120:123]
	v_mfma_f32_16x16x32_bf16 v[108:111], v[158:161], v[208:211], v[108:111]
	v_mfma_f32_16x16x32_bf16 v[104:107], v[166:169], v[208:211], v[104:107]
	v_mfma_f32_16x16x32_bf16 v[92:95], v[158:161], v[216:219], v[92:95]
	v_mfma_f32_16x16x32_bf16 v[88:91], v[166:169], v[216:219], v[88:91]
	v_mfma_f32_16x16x32_bf16 v[76:79], v[158:161], v[224:227], v[76:79]
	v_mfma_f32_16x16x32_bf16 v[72:75], v[166:169], v[224:227], v[72:75]
	s_setprio 0
	s_setprio 1
	v_mfma_f32_16x16x32_bf16 v[116:119], v[170:173], v[196:199], v[116:119]
	v_mfma_f32_16x16x32_bf16 v[112:115], v[188:191], v[196:199], v[112:115]
	v_mfma_f32_16x16x32_bf16 v[100:103], v[170:173], v[204:207], v[100:103]
	v_mfma_f32_16x16x32_bf16 v[96:99], v[188:191], v[204:207], v[96:99]
	v_mfma_f32_16x16x32_bf16 v[84:87], v[170:173], v[212:215], v[84:87]
	v_mfma_f32_16x16x32_bf16 v[80:83], v[188:191], v[212:215], v[80:83]
	v_mfma_f32_16x16x32_bf16 v[68:71], v[170:173], v[220:223], v[68:71]
	v_mfma_f32_16x16x32_bf16 v[64:67], v[188:191], v[220:223], v[64:67]
	v_mfma_f32_16x16x32_bf16 v[116:119], v[174:177], v[200:203], v[116:119]
	v_mfma_f32_16x16x32_bf16 v[112:115], v[192:195], v[200:203], v[112:115]
	v_mfma_f32_16x16x32_bf16 v[100:103], v[174:177], v[208:211], v[100:103]
	v_mfma_f32_16x16x32_bf16 v[96:99], v[192:195], v[208:211], v[96:99]
	v_mfma_f32_16x16x32_bf16 v[84:87], v[174:177], v[216:219], v[84:87]
	v_mfma_f32_16x16x32_bf16 v[80:83], v[192:195], v[216:219], v[80:83]
	v_mfma_f32_16x16x32_bf16 v[68:71], v[174:177], v[224:227], v[68:71]
	v_mfma_f32_16x16x32_bf16 v[64:67], v[192:195], v[224:227], v[64:67]
	s_setprio 0
	s_barrier
	s_add_i32 s2, vcc_hi, s82
	s_add_u32 s98, s76, 0x80
	s_addc_u32 s99, s77, 0
	s_mov_b32 m0, s2
	ds_read_b128 v[196:199], v184 offset:49152
	ds_read_b128 v[200:203], v184 offset:50176
	ds_read_b128 v[204:207], v184 offset:51200
	ds_read_b128 v[208:211], v184 offset:52224
	ds_read_b128 v[212:215], v184 offset:53248
	ds_read_b128 v[216:219], v184 offset:54272
	ds_read_b128 v[220:223], v184 offset:55296
	ds_read_b128 v[224:227], v184 offset:56320
	global_load_lds_dwordx4 v130, s[98:99]
	s_add_i32 m0, s2, 0x2000
	s_add_u32 s2, s76, 0x40080
	s_addc_u32 s3, s77, 0
	s_add_i32 s42, s42, s82
	global_load_lds_dwordx4 v134, s[98:99]
	s_mov_b32 m0, s42
	s_nop 0
	global_load_lds_dwordx4 v130, s[2:3]
	s_add_i32 m0, s42, 0x2000
	s_nop 0
	global_load_lds_dwordx4 v134, s[2:3]
	s_add_u32 s100, s78, 0x80
	s_addc_u32 s101, s79, 0
	s_mov_b32 m0, s87
	s_nop 0
	global_load_lds_dwordx4 v128, s[100:101]
	s_mov_b32 m0, s88
	s_nop 0
	global_load_lds_dwordx4 v132, s[100:101]
	s_waitcnt vmcnt(8)
	s_waitcnt lgkmcnt(0)
	s_barrier
	s_setprio 1
	s_waitcnt lgkmcnt(0)
	v_mfma_f32_16x16x32_bf16 v[60:63], v[154:157], v[196:199], v[60:63]
	v_mfma_f32_16x16x32_bf16 v[56:59], v[162:165], v[196:199], v[56:59]
	v_mfma_f32_16x16x32_bf16 v[44:47], v[154:157], v[204:207], v[44:47]
	v_mfma_f32_16x16x32_bf16 v[40:43], v[162:165], v[204:207], v[40:43]
	v_mfma_f32_16x16x32_bf16 v[28:31], v[154:157], v[212:215], v[28:31]
	v_mfma_f32_16x16x32_bf16 v[24:27], v[162:165], v[212:215], v[24:27]
	v_mfma_f32_16x16x32_bf16 v[12:15], v[154:157], v[220:223], v[12:15]
	v_mfma_f32_16x16x32_bf16 v[8:11], v[162:165], v[220:223], v[8:11]
	v_mfma_f32_16x16x32_bf16 v[60:63], v[158:161], v[200:203], v[60:63]
	v_mfma_f32_16x16x32_bf16 v[56:59], v[166:169], v[200:203], v[56:59]
	v_mfma_f32_16x16x32_bf16 v[44:47], v[158:161], v[208:211], v[44:47]
	v_mfma_f32_16x16x32_bf16 v[40:43], v[166:169], v[208:211], v[40:43]
	v_mfma_f32_16x16x32_bf16 v[28:31], v[158:161], v[216:219], v[28:31]
	v_mfma_f32_16x16x32_bf16 v[24:27], v[166:169], v[216:219], v[24:27]
	v_mfma_f32_16x16x32_bf16 v[12:15], v[158:161], v[224:227], v[12:15]
	v_mfma_f32_16x16x32_bf16 v[8:11], v[166:169], v[224:227], v[8:11]
	s_setprio 0
	s_setprio 1
	v_mfma_f32_16x16x32_bf16 v[52:55], v[170:173], v[196:199], v[52:55]
	v_mfma_f32_16x16x32_bf16 v[48:51], v[188:191], v[196:199], v[48:51]
	v_mfma_f32_16x16x32_bf16 v[36:39], v[170:173], v[204:207], v[36:39]
	v_mfma_f32_16x16x32_bf16 v[32:35], v[188:191], v[204:207], v[32:35]
	v_mfma_f32_16x16x32_bf16 v[20:23], v[170:173], v[212:215], v[20:23]
	v_mfma_f32_16x16x32_bf16 v[16:19], v[188:191], v[212:215], v[16:19]
	v_mfma_f32_16x16x32_bf16 v[4:7], v[170:173], v[220:223], v[4:7]
	v_mfma_f32_16x16x32_bf16 v[0:3], v[188:191], v[220:223], v[0:3]
	v_mfma_f32_16x16x32_bf16 v[52:55], v[174:177], v[200:203], v[52:55]
	v_mfma_f32_16x16x32_bf16 v[48:51], v[192:195], v[200:203], v[48:51]
	v_mfma_f32_16x16x32_bf16 v[36:39], v[174:177], v[208:211], v[36:39]
	v_mfma_f32_16x16x32_bf16 v[32:35], v[192:195], v[208:211], v[32:35]
	v_mfma_f32_16x16x32_bf16 v[20:23], v[174:177], v[216:219], v[20:23]
	v_mfma_f32_16x16x32_bf16 v[16:19], v[192:195], v[216:219], v[16:19]
	v_mfma_f32_16x16x32_bf16 v[4:7], v[174:177], v[224:227], v[4:7]
	v_mfma_f32_16x16x32_bf16 v[0:3], v[192:195], v[224:227], v[0:3]
	s_setprio 0
	s_barrier
	s_add_i32 vcc_lo, vcc_lo, 2
	s_add_u32 s8, s8, 0x100
	s_addc_u32 s9, s9, 0
	s_add_u32 s96, s96, 0x100
	s_addc_u32 s97, s97, 0
	s_cmp_gt_u32 vcc_lo, 13
	s_cbranch_scc0 .LBB0_1645
	s_and_b64 vcc, exec, s[56:57]
	s_cbranch_vccz .LBB0_1648
	s_barrier

; #define PG8_STAGE(bufoff, gbase, voff) do { _Pragma("unroll") for (int _i = 0; _i < 2; ++_i) \
;         __builtin_amdgcn_global_load_lds((const unsigned*)((const char*)(gbase) + (voff)[_i]), (PG8_LAS unsigned*)(lds + (bufoff) + ldsw + _i * 8192), 16, 0, 0); } while (0)
; #define PG8_LDA(dst, b, h) do { _Pragma("unroll") for (int m = 0; m < 4; ++m) _Pragma("unroll") for (int k = 0; k < 2; ++k) dst[m][k] = *(const PG8_LAS bf16x8*)(lds + PG8_SA(b, h) + aoff + m * 2048 + k * 1024); } while (0)
; #define PG8_LDB(dst, b, h) do { _Pragma("unroll") for (int n = 0; n < 2; ++n) _Pragma("unroll") for (int k = 0; k < 2; ++k) dst[n][k] = *(const PG8_LAS bf16x8*)(lds + PG8_SB(b, h) + boff + n * 2048 + k * 1024); } while (0)
; #define PG8_MMA(ai, bj, At, Bt) do { __builtin_amdgcn_s_setprio(1); _Pragma("unroll") for (int m = 0; m < 4; ++m) _Pragma("unroll") for (int n = 0; n < 2; ++n) _Pragma("unroll") for (int k = 0; k < 2; ++k) \
;         acc[ai][bj][m][n] = __builtin_amdgcn_mfma_f32_16x16x32_bf16(Bt[n][k], At[m][k], acc[ai][bj][m][n], 0, 0, 0); __builtin_amdgcn_s_setprio(0); } while (0)
; #define PG8_WAIT_V(n) asm volatile("s_waitcnt vmcnt(" #n ")" ::: "memory")
; #define PG8_WAIT_L(n) asm volatile("s_waitcnt lgkmcnt(" #n ")" ::: "memory")
; #define PG8_BAR __builtin_amdgcn_s_barrier()
; #define PG8_SCHED __builtin_amdgcn_sched_barrier(0)
; template <class Epi, class Sched, bool ALIGN_EPI = false, bool SP2 = false>
; __device__ __forceinline__ void gemm_phase(PG8_LAS unsigned char* lds, const Gemm g, const Sched& S, const Epi& E, int wv) {
;     ...
;             PG8_LDB(B0, 0, 0); PG8_LDB(B1, 0, 1); PG8_SCHED; PG8_LDA(At, 0, 0); PG8_STAGE(PG8_SA(1, 1), a1 + hstepA, voffA);
;             PG8_WAIT_V(8); PG8_WAIT_L(0); PG8_BAR; PG8_MMA(0, 0, At, B0); PG8_MMA(0, 1, At, B1); PG8_BAR; PG8_SCHED;
;             PG8_LDA(At, 0, 1); PG8_STAGE(PG8_SB(0, 0), b2, voffB); PG8_STAGE(PG8_SB(0, 1), b2 + hstepB, voffB); PG8_STAGE(PG8_SA(0, 0), a2, voffA);
;             PG8_WAIT_V(8); PG8_WAIT_L(0); PG8_BAR; PG8_MMA(1, 0, At, B0); PG8_MMA(1, 1, At, B1); PG8_BAR; PG8_SCHED;
.LBB0_2016:
	ds_read_b128 v[144:147], v153
	ds_read_b128 v[156:159], v153 offset:1024
	ds_read_b128 v[160:163], v153 offset:2048
	ds_read_b128 v[164:167], v153 offset:3072
	ds_read_b128 v[168:171], v154
	ds_read_b128 v[172:175], v154 offset:1024
	ds_read_b128 v[176:179], v154 offset:2048
	ds_read_b128 v[180:183], v154 offset:3072
	s_add_u32 s0, s38, 0xfffc0080
	s_addc_u32 s1, s39, -1
	s_cmp_eq_u32 s62, 12
	s_cselect_b32 s43, s23, s1
	s_cselect_b32 s42, s29, s0
	s_cselect_b32 s41, s21, s59
	s_cselect_b32 s40, s57, s58
	s_add_i32 m0, s37, 0xc000
	ds_read_b128 v[184:187], v155
	ds_read_b128 v[188:191], v155 offset:1024
	ds_read_b128 v[192:195], v155 offset:2048
	ds_read_b128 v[196:199], v155 offset:3072
	ds_read_b128 v[200:203], v155 offset:4096
	ds_read_b128 v[204:207], v155 offset:5120
	ds_read_b128 v[208:211], v155 offset:6144
	ds_read_b128 v[212:215], v155 offset:7168
	global_load_lds_dwordx4 v136, s[38:39]
	s_add_i32 m0, s37, 0xe000
	s_nop 0
	global_load_lds_dwordx4 v138, s[38:39]
	s_waitcnt vmcnt(8)
	s_waitcnt lgkmcnt(0)
	s_barrier
	s_setprio 1
	s_waitcnt lgkmcnt(0)
	v_mfma_f32_16x16x32_bf16 v[124:127], v[144:147], v[184:187], v[124:127]
	v_mfma_f32_16x16x32_bf16 v[120:123], v[160:163], v[184:187], v[120:123]
	v_mfma_f32_16x16x32_bf16 v[108:111], v[144:147], v[192:195], v[108:111]
	v_mfma_f32_16x16x32_bf16 v[104:107], v[160:163], v[192:195], v[104:107]
	v_mfma_f32_16x16x32_bf16 v[92:95], v[144:147], v[200:203], v[92:95]
	v_mfma_f32_16x16x32_bf16 v[88:91], v[160:163], v[200:203], v[88:91]
	v_mfma_f32_16x16x32_bf16 v[76:79], v[144:147], v[208:211], v[76:79]
	v_mfma_f32_16x16x32_bf16 v[72:75], v[160:163], v[208:211], v[72:75]
	v_mfma_f32_16x16x32_bf16 v[124:127], v[156:159], v[188:191], v[124:127]
	v_mfma_f32_16x16x32_bf16 v[120:123], v[164:167], v[188:191], v[120:123]
	v_mfma_f32_16x16x32_bf16 v[108:111], v[156:159], v[196:199], v[108:111]
	v_mfma_f32_16x16x32_bf16 v[104:107], v[164:167], v[196:199], v[104:107]
	v_mfma_f32_16x16x32_bf16 v[92:95], v[156:159], v[204:207], v[92:95]
	v_mfma_f32_16x16x32_bf16 v[88:91], v[164:167], v[204:207], v[88:91]
	v_mfma_f32_16x16x32_bf16 v[76:79], v[156:159], v[212:215], v[76:79]
	v_mfma_f32_16x16x32_bf16 v[72:75], v[164:167], v[212:215], v[72:75]
	s_setprio 0
	s_setprio 1
	v_mfma_f32_16x16x32_bf16 v[116:119], v[168:171], v[184:187], v[116:119]
	v_mfma_f32_16x16x32_bf16 v[112:115], v[176:179], v[184:187], v[112:115]
	v_mfma_f32_16x16x32_bf16 v[100:103], v[168:171], v[192:195], v[100:103]
	v_mfma_f32_16x16x32_bf16 v[96:99], v[176:179], v[192:195], v[96:99]
	v_mfma_f32_16x16x32_bf16 v[84:87], v[168:171], v[200:203], v[84:87]
	v_mfma_f32_16x16x32_bf16 v[80:83], v[176:179], v[200:203], v[80:83]
	v_mfma_f32_16x16x32_bf16 v[68:71], v[168:171], v[208:211], v[68:71]
	v_mfma_f32_16x16x32_bf16 v[64:67], v[176:179], v[208:211], v[64:67]
	v_mfma_f32_16x16x32_bf16 v[116:119], v[172:175], v[188:191], v[116:119]
	v_mfma_f32_16x16x32_bf16 v[112:115], v[180:183], v[188:191], v[112:115]
	v_mfma_f32_16x16x32_bf16 v[100:103], v[172:175], v[196:199], v[100:103]
	v_mfma_f32_16x16x32_bf16 v[96:99], v[180:183], v[196:199], v[96:99]
	v_mfma_f32_16x16x32_bf16 v[84:87], v[172:175], v[204:207], v[84:87]
	v_mfma_f32_16x16x32_bf16 v[80:83], v[180:183], v[204:207], v[80:83]
	v_mfma_f32_16x16x32_bf16 v[68:71], v[172:175], v[212:215], v[68:71]
	v_mfma_f32_16x16x32_bf16 v[64:67], v[180:183], v[212:215], v[64:67]
	s_setprio 0
	s_barrier
	s_add_i32 s0, s55, s46
	s_mov_b32 m0, s0
	ds_read_b128 v[184:187], v155 offset:16384
	ds_read_b128 v[188:191], v155 offset:17408
	ds_read_b128 v[192:195], v155 offset:18432
	ds_read_b128 v[196:199], v155 offset:19456
	ds_read_b128 v[200:203], v155 offset:20480
	ds_read_b128 v[204:207], v155 offset:21504
	ds_read_b128 v[208:211], v155 offset:22528
	ds_read_b128 v[212:215], v155 offset:23552
	global_load_lds_dwordx4 v130, s[40:41]
	s_add_i32 m0, s0, 0x2000
	s_add_u32 s0, s40, 0x40000
	s_addc_u32 s1, s41, 0
	s_add_i32 s63, s56, s46
	global_load_lds_dwordx4 v134, s[40:41]
	s_mov_b32 m0, s63
	s_nop 0
	global_load_lds_dwordx4 v130, s[0:1]
	s_add_i32 m0, s63, 0x2000
	s_nop 0
	global_load_lds_dwordx4 v134, s[0:1]
	s_mov_b32 m0, s37
	s_nop 0
	global_load_lds_dwordx4 v128, s[42:43]
	s_mov_b32 m0, s47
	s_nop 0
	global_load_lds_dwordx4 v132, s[42:43]
	s_waitcnt vmcnt(8)
	s_waitcnt lgkmcnt(0)
	s_barrier
	s_setprio 1
	s_waitcnt lgkmcnt(0)
	v_mfma_f32_16x16x32_bf16 v[60:63], v[144:147], v[184:187], v[60:63]
	v_mfma_f32_16x16x32_bf16 v[56:59], v[160:163], v[184:187], v[56:59]
	v_mfma_f32_16x16x32_bf16 v[44:47], v[144:147], v[192:195], v[44:47]
	v_mfma_f32_16x16x32_bf16 v[40:43], v[160:163], v[192:195], v[40:43]
	v_mfma_f32_16x16x32_bf16 v[28:31], v[144:147], v[200:203], v[28:31]
	v_mfma_f32_16x16x32_bf16 v[24:27], v[160:163], v[200:203], v[24:27]
	v_mfma_f32_16x16x32_bf16 v[12:15], v[144:147], v[208:211], v[12:15]
	v_mfma_f32_16x16x32_bf16 v[8:11], v[160:163], v[208:211], v[8:11]
	v_mfma_f32_16x16x32_bf16 v[60:63], v[156:159], v[188:191], v[60:63]
	v_mfma_f32_16x16x32_bf16 v[56:59], v[164:167], v[188:191], v[56:59]
	v_mfma_f32_16x16x32_bf16 v[44:47], v[156:159], v[196:199], v[44:47]
	v_mfma_f32_16x16x32_bf16 v[40:43], v[164:167], v[196:199], v[40:43]
	v_mfma_f32_16x16x32_bf16 v[28:31], v[156:159], v[204:207], v[28:31]
	v_mfma_f32_16x16x32_bf16 v[24:27], v[164:167], v[204:207], v[24:27]
	v_mfma_f32_16x16x32_bf16 v[12:15], v[156:159], v[212:215], v[12:15]
	v_mfma_f32_16x16x32_bf16 v[8:11], v[164:167], v[212:215], v[8:11]
	s_setprio 0
	s_setprio 1
	v_mfma_f32_16x16x32_bf16 v[52:55], v[168:171], v[184:187], v[52:55]
	v_mfma_f32_16x16x32_bf16 v[48:51], v[176:179], v[184:187], v[48:51]
	v_mfma_f32_16x16x32_bf16 v[36:39], v[168:171], v[192:195], v[36:39]
	v_mfma_f32_16x16x32_bf16 v[32:35], v[176:179], v[192:195], v[32:35]
	v_mfma_f32_16x16x32_bf16 v[20:23], v[168:171], v[200:203], v[20:23]
	v_mfma_f32_16x16x32_bf16 v[16:19], v[176:179], v[200:203], v[16:19]
	v_mfma_f32_16x16x32_bf16 v[4:7], v[168:171], v[208:211], v[4:7]
	v_mfma_f32_16x16x32_bf16 v[0:3], v[176:179], v[208:211], v[0:3]
	v_mfma_f32_16x16x32_bf16 v[52:55], v[172:175], v[188:191], v[52:55]
	v_mfma_f32_16x16x32_bf16 v[48:51], v[180:183], v[188:191], v[48:51]
	v_mfma_f32_16x16x32_bf16 v[36:39], v[172:175], v[196:199], v[36:39]
	v_mfma_f32_16x16x32_bf16 v[32:35], v[180:183], v[196:199], v[32:35]
	v_mfma_f32_16x16x32_bf16 v[20:23], v[172:175], v[204:207], v[20:23]
	v_mfma_f32_16x16x32_bf16 v[16:19], v[180:183], v[204:207], v[16:19]
	v_mfma_f32_16x16x32_bf16 v[4:7], v[172:175], v[212:215], v[4:7]
	v_mfma_f32_16x16x32_bf16 v[0:3], v[180:183], v[212:215], v[0:3]
	s_setprio 0
	s_barrier
; #define PG8_STAGE(bufoff, gbase, voff) do { _Pragma("unroll") for (int _i = 0; _i < 2; ++_i) \
;         __builtin_amdgcn_global_load_lds((const unsigned*)((const char*)(gbase) + (voff)[_i]), (PG8_LAS unsigned*)(lds + (bufoff) + ldsw + _i * 8192), 16, 0, 0); } while (0)
; #define PG8_LDA(dst, b, h) do { _Pragma("unroll") for (int m = 0; m < 4; ++m) _Pragma("unroll") for (int k = 0; k < 2; ++k) dst[m][k] = *(const PG8_LAS bf16x8*)(lds + PG8_SA(b, h) + aoff + m * 2048 + k * 1024); } while (0)
; #define PG8_LDB(dst, b, h) do { _Pragma("unroll") for (int n = 0; n < 2; ++n) _Pragma("unroll") for (int k = 0; k < 2; ++k) dst[n][k] = *(const PG8_LAS bf16x8*)(lds + PG8_SB(b, h) + boff + n * 2048 + k * 1024); } while (0)
; #define PG8_MMA(ai, bj, At, Bt) do { __builtin_amdgcn_s_setprio(1); _Pragma("unroll") for (int m = 0; m < 4; ++m) _Pragma("unroll") for (int n = 0; n < 2; ++n) _Pragma("unroll") for (int k = 0; k < 2; ++k) \
;         acc[ai][bj][m][n] = __builtin_amdgcn_mfma_f32_16x16x32_bf16(Bt[n][k], At[m][k], acc[ai][bj][m][n], 0, 0, 0); __builtin_amdgcn_s_setprio(0); } while (0)
; #define PG8_WAIT_V(n) asm volatile("s_waitcnt vmcnt(" #n ")" ::: "memory")
; #define PG8_WAIT_L(n) asm volatile("s_waitcnt lgkmcnt(" #n ")" ::: "memory")
; #define PG8_BAR __builtin_amdgcn_s_barrier()
; template <class Epi, class Sched, bool ALIGN_EPI = false, bool SP2 = false>
; __device__ __forceinline__ void gemm_phase(PG8_LAS unsigned char* lds, const Gemm g, const Sched& S, const Epi& E, int wv) {
;     ...
;         for (int t = 0; t < nt; t += 2) {
;             const bool last = (t == nt - 2);
;             const char* a1 = cA + (size_t)(t + 1) * kstep;
;             const char* a2 = last ? nA : cA + (size_t)(t + 2) * kstep; const char* b2 = last ? nB : cB + (size_t)(t + 2) * kstep;
;             const char* a3 = a2 + kstep; const char* b3 = b2 + kstep;
;     ...
;             PG8_LDB(B0, 1, 0); PG8_LDB(B1, 1, 1); PG8_SCHED; PG8_LDA(At, 1, 0); PG8_STAGE(PG8_SA(0, 1), a2 + hstepA, voffA);
;             PG8_WAIT_V(8); PG8_WAIT_L(0); PG8_BAR; PG8_MMA(0, 0, At, B0); PG8_MMA(0, 1, At, B1); PG8_BAR; PG8_SCHED;
;             PG8_LDA(At, 1, 1); PG8_STAGE(PG8_SB(1, 0), b3, voffB); PG8_STAGE(PG8_SB(1, 1), b3 + hstepB, voffB); PG8_STAGE(PG8_SA(1, 0), a3, voffA);
;             PG8_WAIT_V(8); PG8_WAIT_L(0); PG8_BAR; PG8_MMA(1, 0, At, B0); PG8_MMA(1, 1, At, B1); PG8_BAR; PG8_SCHED;
	s_add_i32 s63, 0, 0x18000
	s_add_i32 s64, 0, 0x1c000
	v_add_u32_e32 v164, s63, v149
	v_add_u32_e32 v180, s64, v149
	ds_read_b128 v[144:147], v164
	ds_read_b128 v[156:159], v164 offset:1024
	ds_read_b128 v[160:163], v164 offset:2048
	ds_read_b128 v[164:167], v164 offset:3072
	ds_read_b128 v[168:171], v180
	ds_read_b128 v[172:175], v180 offset:1024
	ds_read_b128 v[176:179], v180 offset:2048
	ds_read_b128 v[180:183], v180 offset:3072
	s_add_u32 s0, s42, 0x40000
	s_addc_u32 s1, s43, 0
	s_mov_b32 m0, s48
	ds_read_b128 v[184:187], v155 offset:32768
	ds_read_b128 v[188:191], v155 offset:33792
	ds_read_b128 v[192:195], v155 offset:34816
	ds_read_b128 v[196:199], v155 offset:35840
	ds_read_b128 v[200:203], v155 offset:36864
	ds_read_b128 v[204:207], v155 offset:37888
	ds_read_b128 v[208:211], v155 offset:38912
	ds_read_b128 v[212:215], v155 offset:39936
	global_load_lds_dwordx4 v128, s[0:1]
	s_mov_b32 m0, s49
	s_nop 0
	global_load_lds_dwordx4 v132, s[0:1]
	s_waitcnt vmcnt(8)
	s_waitcnt lgkmcnt(0)
	s_barrier
	s_setprio 1
	s_waitcnt lgkmcnt(0)
	v_mfma_f32_16x16x32_bf16 v[124:127], v[144:147], v[184:187], v[124:127]
	v_mfma_f32_16x16x32_bf16 v[120:123], v[160:163], v[184:187], v[120:123]
	v_mfma_f32_16x16x32_bf16 v[108:111], v[144:147], v[192:195], v[108:111]
	v_mfma_f32_16x16x32_bf16 v[104:107], v[160:163], v[192:195], v[104:107]
	v_mfma_f32_16x16x32_bf16 v[92:95], v[144:147], v[200:203], v[92:95]
	v_mfma_f32_16x16x32_bf16 v[88:91], v[160:163], v[200:203], v[88:91]
	v_mfma_f32_16x16x32_bf16 v[76:79], v[144:147], v[208:211], v[76:79]
	v_mfma_f32_16x16x32_bf16 v[72:75], v[160:163], v[208:211], v[72:75]
	v_mfma_f32_16x16x32_bf16 v[124:127], v[156:159], v[188:191], v[124:127]
	v_mfma_f32_16x16x32_bf16 v[120:123], v[164:167], v[188:191], v[120:123]
	v_mfma_f32_16x16x32_bf16 v[108:111], v[156:159], v[196:199], v[108:111]
	v_mfma_f32_16x16x32_bf16 v[104:107], v[164:167], v[196:199], v[104:107]
	v_mfma_f32_16x16x32_bf16 v[92:95], v[156:159], v[204:207], v[92:95]
	v_mfma_f32_16x16x32_bf16 v[88:91], v[164:167], v[204:207], v[88:91]
	v_mfma_f32_16x16x32_bf16 v[76:79], v[156:159], v[212:215], v[76:79]
	v_mfma_f32_16x16x32_bf16 v[72:75], v[164:167], v[212:215], v[72:75]
	s_setprio 0
	s_setprio 1
	v_mfma_f32_16x16x32_bf16 v[116:119], v[168:171], v[184:187], v[116:119]
	v_mfma_f32_16x16x32_bf16 v[112:115], v[176:179], v[184:187], v[112:115]
	v_mfma_f32_16x16x32_bf16 v[100:103], v[168:171], v[192:195], v[100:103]
	v_mfma_f32_16x16x32_bf16 v[96:99], v[176:179], v[192:195], v[96:99]
	v_mfma_f32_16x16x32_bf16 v[84:87], v[168:171], v[200:203], v[84:87]
	v_mfma_f32_16x16x32_bf16 v[80:83], v[176:179], v[200:203], v[80:83]
	v_mfma_f32_16x16x32_bf16 v[68:71], v[168:171], v[208:211], v[68:71]
	v_mfma_f32_16x16x32_bf16 v[64:67], v[176:179], v[208:211], v[64:67]
	v_mfma_f32_16x16x32_bf16 v[116:119], v[172:175], v[188:191], v[116:119]
	v_mfma_f32_16x16x32_bf16 v[112:115], v[180:183], v[188:191], v[112:115]
	v_mfma_f32_16x16x32_bf16 v[100:103], v[172:175], v[196:199], v[100:103]
	v_mfma_f32_16x16x32_bf16 v[96:99], v[180:183], v[196:199], v[96:99]
	v_mfma_f32_16x16x32_bf16 v[84:87], v[172:175], v[204:207], v[84:87]
	v_mfma_f32_16x16x32_bf16 v[80:83], v[180:183], v[204:207], v[80:83]
	v_mfma_f32_16x16x32_bf16 v[68:71], v[172:175], v[212:215], v[68:71]
	v_mfma_f32_16x16x32_bf16 v[64:67], v[180:183], v[212:215], v[64:67]
	s_setprio 0
	s_barrier
	s_add_i32 s0, s63, s46
	s_add_u32 s76, s40, 0x80
	s_addc_u32 s77, s41, 0
	s_mov_b32 m0, s0
	ds_read_b128 v[184:187], v155 offset:49152
	ds_read_b128 v[188:191], v155 offset:50176
	ds_read_b128 v[192:195], v155 offset:51200
	ds_read_b128 v[196:199], v155 offset:52224
	ds_read_b128 v[200:203], v155 offset:53248
	ds_read_b128 v[204:207], v155 offset:54272
	ds_read_b128 v[208:211], v155 offset:55296
	ds_read_b128 v[212:215], v155 offset:56320
	global_load_lds_dwordx4 v130, s[76:77]
	s_add_i32 m0, s0, 0x2000
	s_add_u32 s0, s40, 0x40080
	s_addc_u32 s1, s41, 0
	s_add_i32 s40, s64, s46
	global_load_lds_dwordx4 v134, s[76:77]
	s_mov_b32 m0, s40
	s_nop 0
	global_load_lds_dwordx4 v130, s[0:1]
	s_add_i32 m0, s40, 0x2000
	s_nop 0
	global_load_lds_dwordx4 v134, s[0:1]
	s_add_u32 s78, s42, 0x80
	s_addc_u32 s79, s43, 0
	s_mov_b32 m0, s51
	s_nop 0
	global_load_lds_dwordx4 v128, s[78:79]
	s_mov_b32 m0, s52
	s_nop 0
	global_load_lds_dwordx4 v132, s[78:79]
	s_waitcnt vmcnt(8)
	s_waitcnt lgkmcnt(0)
	s_barrier
	s_setprio 1
	s_waitcnt lgkmcnt(0)
	v_mfma_f32_16x16x32_bf16 v[60:63], v[144:147], v[184:187], v[60:63]
	v_mfma_f32_16x16x32_bf16 v[56:59], v[160:163], v[184:187], v[56:59]
	v_mfma_f32_16x16x32_bf16 v[44:47], v[144:147], v[192:195], v[44:47]
	v_mfma_f32_16x16x32_bf16 v[40:43], v[160:163], v[192:195], v[40:43]
	v_mfma_f32_16x16x32_bf16 v[28:31], v[144:147], v[200:203], v[28:31]
	v_mfma_f32_16x16x32_bf16 v[24:27], v[160:163], v[200:203], v[24:27]
	v_mfma_f32_16x16x32_bf16 v[12:15], v[144:147], v[208:211], v[12:15]
	v_mfma_f32_16x16x32_bf16 v[8:11], v[160:163], v[208:211], v[8:11]
	v_mfma_f32_16x16x32_bf16 v[60:63], v[156:159], v[188:191], v[60:63]
	v_mfma_f32_16x16x32_bf16 v[56:59], v[164:167], v[188:191], v[56:59]
	v_mfma_f32_16x16x32_bf16 v[44:47], v[156:159], v[196:199], v[44:47]
	v_mfma_f32_16x16x32_bf16 v[40:43], v[164:167], v[196:199], v[40:43]
	v_mfma_f32_16x16x32_bf16 v[28:31], v[156:159], v[204:207], v[28:31]
	v_mfma_f32_16x16x32_bf16 v[24:27], v[164:167], v[204:207], v[24:27]
	v_mfma_f32_16x16x32_bf16 v[12:15], v[156:159], v[212:215], v[12:15]
	v_mfma_f32_16x16x32_bf16 v[8:11], v[164:167], v[212:215], v[8:11]
	s_setprio 0
	s_setprio 1
	v_mfma_f32_16x16x32_bf16 v[52:55], v[168:171], v[184:187], v[52:55]
	v_mfma_f32_16x16x32_bf16 v[48:51], v[176:179], v[184:187], v[48:51]
	v_mfma_f32_16x16x32_bf16 v[36:39], v[168:171], v[192:195], v[36:39]
	v_mfma_f32_16x16x32_bf16 v[32:35], v[176:179], v[192:195], v[32:35]
	v_mfma_f32_16x16x32_bf16 v[20:23], v[168:171], v[200:203], v[20:23]
	v_mfma_f32_16x16x32_bf16 v[16:19], v[176:179], v[200:203], v[16:19]
	v_mfma_f32_16x16x32_bf16 v[4:7], v[168:171], v[208:211], v[4:7]
	v_mfma_f32_16x16x32_bf16 v[0:3], v[176:179], v[208:211], v[0:3]
	v_mfma_f32_16x16x32_bf16 v[52:55], v[172:175], v[188:191], v[52:55]
	v_mfma_f32_16x16x32_bf16 v[48:51], v[180:183], v[188:191], v[48:51]
	v_mfma_f32_16x16x32_bf16 v[36:39], v[172:175], v[196:199], v[36:39]
	v_mfma_f32_16x16x32_bf16 v[32:35], v[180:183], v[196:199], v[32:35]
	v_mfma_f32_16x16x32_bf16 v[20:23], v[172:175], v[204:207], v[20:23]
	v_mfma_f32_16x16x32_bf16 v[16:19], v[180:183], v[204:207], v[16:19]
	v_mfma_f32_16x16x32_bf16 v[4:7], v[172:175], v[212:215], v[4:7]
	v_mfma_f32_16x16x32_bf16 v[0:3], v[180:183], v[212:215], v[0:3]
	s_setprio 0
	s_barrier
	s_add_i32 s62, s62, 2
	s_add_u32 s38, s38, 0x100
	s_addc_u32 s39, s39, 0
	s_add_u32 s58, s58, 0x100
	s_addc_u32 s59, s59, 0
	s_cmp_gt_u32 s62, 13
	s_cbranch_scc0 .LBB0_2016
	s_and_b64 vcc, exec, s[18:19]
	s_cbranch_vccz .LBB0_2019
	s_barrier

; #define PG8_STAGE(bufoff, gbase, voff) do { _Pragma("unroll") for (int _i = 0; _i < 2; ++_i) \
;         __builtin_amdgcn_global_load_lds((const unsigned*)((const char*)(gbase) + (voff)[_i]), (PG8_LAS unsigned*)(lds + (bufoff) + ldsw + _i * 8192), 16, 0, 0); } while (0)
; #define PG8_LDA(dst, b, h) do { _Pragma("unroll") for (int m = 0; m < 4; ++m) _Pragma("unroll") for (int k = 0; k < 2; ++k) dst[m][k] = *(const PG8_LAS bf16x8*)(lds + PG8_SA(b, h) + aoff + m * 2048 + k * 1024); } while (0)
; #define PG8_LDB(dst, b, h) do { _Pragma("unroll") for (int n = 0; n < 2; ++n) _Pragma("unroll") for (int k = 0; k < 2; ++k) dst[n][k] = *(const PG8_LAS bf16x8*)(lds + PG8_SB(b, h) + boff + n * 2048 + k * 1024); } while (0)
; #define PG8_MMA(ai, bj, At, Bt) do { __builtin_amdgcn_s_setprio(1); _Pragma("unroll") for (int m = 0; m < 4; ++m) _Pragma("unroll") for (int n = 0; n < 2; ++n) _Pragma("unroll") for (int k = 0; k < 2; ++k) \
;         acc[ai][bj][m][n] = __builtin_amdgcn_mfma_f32_16x16x32_bf16(Bt[n][k], At[m][k], acc[ai][bj][m][n], 0, 0, 0); __builtin_amdgcn_s_setprio(0); } while (0)
; #define PG8_WAIT_V(n) asm volatile("s_waitcnt vmcnt(" #n ")" ::: "memory")
; #define PG8_WAIT_L(n) asm volatile("s_waitcnt lgkmcnt(" #n ")" ::: "memory")
; #define PG8_BAR __builtin_amdgcn_s_barrier()
; #define PG8_SCHED __builtin_amdgcn_sched_barrier(0)
; template <class Epi, class Sched, bool ALIGN_EPI = false, bool SP2 = false>
; __device__ __forceinline__ void gemm_phase(PG8_LAS unsigned char* lds, const Gemm g, const Sched& S, const Epi& E, int wv) {
;     ...
;             PG8_LDB(B0, 0, 0); PG8_LDB(B1, 0, 1); PG8_SCHED; PG8_LDA(At, 0, 0); PG8_STAGE(PG8_SA(1, 1), a1 + hstepA, voffA);
;             PG8_WAIT_V(8); PG8_WAIT_L(0); PG8_BAR; PG8_MMA(0, 0, At, B0); PG8_MMA(0, 1, At, B1); PG8_BAR; PG8_SCHED;
;             PG8_LDA(At, 0, 1); PG8_STAGE(PG8_SB(0, 0), b2, voffB); PG8_STAGE(PG8_SB(0, 1), b2 + hstepB, voffB); PG8_STAGE(PG8_SA(0, 0), a2, voffA);
;             PG8_WAIT_V(8); PG8_WAIT_L(0); PG8_BAR; PG8_MMA(1, 0, At, B0); PG8_MMA(1, 1, At, B1); PG8_BAR; PG8_SCHED;
.LBB0_2067:
	ds_read_b128 v[144:147], v155
	ds_read_b128 v[148:151], v155 offset:1024
	ds_read_b128 v[160:163], v155 offset:2048
	ds_read_b128 v[164:167], v155 offset:3072
	ds_read_b128 v[168:171], v156
	ds_read_b128 v[172:175], v156 offset:1024
	ds_read_b128 v[176:179], v156 offset:2048
	ds_read_b128 v[180:183], v156 offset:3072
	s_add_u32 s0, s42, 0xfffc0080
	s_addc_u32 s1, s43, -1
	s_cmp_eq_u32 s71, 12
	s_cselect_b32 s47, s37, s1
	s_cselect_b32 s46, s67, s0
	s_cselect_b32 s45, s29, s70
	s_cselect_b32 s44, s68, s69
	s_add_i32 m0, s52, 0xc000
	ds_read_b128 v[184:187], v157
	ds_read_b128 v[188:191], v157 offset:1024
	ds_read_b128 v[192:195], v157 offset:2048
	ds_read_b128 v[196:199], v157 offset:3072
	ds_read_b128 v[200:203], v157 offset:4096
	ds_read_b128 v[204:207], v157 offset:5120
	ds_read_b128 v[208:211], v157 offset:6144
	ds_read_b128 v[212:215], v157 offset:7168
	global_load_lds_dwordx4 v136, s[42:43]
	s_add_i32 m0, s52, 0xe000
	s_nop 0
	global_load_lds_dwordx4 v138, s[42:43]
	s_waitcnt vmcnt(8)
	s_waitcnt lgkmcnt(0)
	s_barrier
	s_setprio 1
	s_waitcnt lgkmcnt(0)
	v_mfma_f32_16x16x32_bf16 v[124:127], v[144:147], v[184:187], v[124:127]
	v_mfma_f32_16x16x32_bf16 v[120:123], v[160:163], v[184:187], v[120:123]
	v_mfma_f32_16x16x32_bf16 v[108:111], v[144:147], v[192:195], v[108:111]
	v_mfma_f32_16x16x32_bf16 v[104:107], v[160:163], v[192:195], v[104:107]
	v_mfma_f32_16x16x32_bf16 v[92:95], v[144:147], v[200:203], v[92:95]
	v_mfma_f32_16x16x32_bf16 v[88:91], v[160:163], v[200:203], v[88:91]
	v_mfma_f32_16x16x32_bf16 v[76:79], v[144:147], v[208:211], v[76:79]
	v_mfma_f32_16x16x32_bf16 v[72:75], v[160:163], v[208:211], v[72:75]
	v_mfma_f32_16x16x32_bf16 v[124:127], v[148:151], v[188:191], v[124:127]
	v_mfma_f32_16x16x32_bf16 v[120:123], v[164:167], v[188:191], v[120:123]
	v_mfma_f32_16x16x32_bf16 v[108:111], v[148:151], v[196:199], v[108:111]
	v_mfma_f32_16x16x32_bf16 v[104:107], v[164:167], v[196:199], v[104:107]
	v_mfma_f32_16x16x32_bf16 v[92:95], v[148:151], v[204:207], v[92:95]
	v_mfma_f32_16x16x32_bf16 v[88:91], v[164:167], v[204:207], v[88:91]
	v_mfma_f32_16x16x32_bf16 v[76:79], v[148:151], v[212:215], v[76:79]
	v_mfma_f32_16x16x32_bf16 v[72:75], v[164:167], v[212:215], v[72:75]
	s_setprio 0
	s_setprio 1
	v_mfma_f32_16x16x32_bf16 v[116:119], v[168:171], v[184:187], v[116:119]
	v_mfma_f32_16x16x32_bf16 v[112:115], v[176:179], v[184:187], v[112:115]
	v_mfma_f32_16x16x32_bf16 v[100:103], v[168:171], v[192:195], v[100:103]
	v_mfma_f32_16x16x32_bf16 v[96:99], v[176:179], v[192:195], v[96:99]
	v_mfma_f32_16x16x32_bf16 v[84:87], v[168:171], v[200:203], v[84:87]
	v_mfma_f32_16x16x32_bf16 v[80:83], v[176:179], v[200:203], v[80:83]
	v_mfma_f32_16x16x32_bf16 v[68:71], v[168:171], v[208:211], v[68:71]
	v_mfma_f32_16x16x32_bf16 v[64:67], v[176:179], v[208:211], v[64:67]
	v_mfma_f32_16x16x32_bf16 v[116:119], v[172:175], v[188:191], v[116:119]
	v_mfma_f32_16x16x32_bf16 v[112:115], v[180:183], v[188:191], v[112:115]
	v_mfma_f32_16x16x32_bf16 v[100:103], v[172:175], v[196:199], v[100:103]
	v_mfma_f32_16x16x32_bf16 v[96:99], v[180:183], v[196:199], v[96:99]
	v_mfma_f32_16x16x32_bf16 v[84:87], v[172:175], v[204:207], v[84:87]
	v_mfma_f32_16x16x32_bf16 v[80:83], v[180:183], v[204:207], v[80:83]
	v_mfma_f32_16x16x32_bf16 v[68:71], v[172:175], v[212:215], v[68:71]
	v_mfma_f32_16x16x32_bf16 v[64:67], v[180:183], v[212:215], v[64:67]
	s_setprio 0
	s_barrier
	s_add_i32 s0, s60, s51
	s_mov_b32 m0, s0
	ds_read_b128 v[184:187], v157 offset:16384
	ds_read_b128 v[188:191], v157 offset:17408
	ds_read_b128 v[192:195], v157 offset:18432
	ds_read_b128 v[196:199], v157 offset:19456
	ds_read_b128 v[200:203], v157 offset:20480
	ds_read_b128 v[204:207], v157 offset:21504
	ds_read_b128 v[208:211], v157 offset:22528
	ds_read_b128 v[212:215], v157 offset:23552
	global_load_lds_dwordx4 v130, s[44:45]
	s_add_i32 m0, s0, 0x2000
	s_add_u32 s0, s44, 0x40000
	s_addc_u32 s1, s45, 0
	s_add_i32 s72, s61, s51
	global_load_lds_dwordx4 v134, s[44:45]
	s_mov_b32 m0, s72
	s_nop 0
	global_load_lds_dwordx4 v130, s[0:1]
	s_add_i32 m0, s72, 0x2000
	s_nop 0
	global_load_lds_dwordx4 v134, s[0:1]
	s_mov_b32 m0, s52
	s_nop 0
	global_load_lds_dwordx4 v128, s[46:47]
	s_mov_b32 m0, s53
	s_nop 0
	global_load_lds_dwordx4 v132, s[46:47]
	s_waitcnt vmcnt(8)
	s_waitcnt lgkmcnt(0)
	s_barrier
	s_setprio 1
	s_waitcnt lgkmcnt(0)
	v_mfma_f32_16x16x32_bf16 v[60:63], v[144:147], v[184:187], v[60:63]
	v_mfma_f32_16x16x32_bf16 v[56:59], v[160:163], v[184:187], v[56:59]
	v_mfma_f32_16x16x32_bf16 v[44:47], v[144:147], v[192:195], v[44:47]
	v_mfma_f32_16x16x32_bf16 v[40:43], v[160:163], v[192:195], v[40:43]
	v_mfma_f32_16x16x32_bf16 v[28:31], v[144:147], v[200:203], v[28:31]
	v_mfma_f32_16x16x32_bf16 v[24:27], v[160:163], v[200:203], v[24:27]
	v_mfma_f32_16x16x32_bf16 v[12:15], v[144:147], v[208:211], v[12:15]
	v_mfma_f32_16x16x32_bf16 v[8:11], v[160:163], v[208:211], v[8:11]
	v_mfma_f32_16x16x32_bf16 v[60:63], v[148:151], v[188:191], v[60:63]
	v_mfma_f32_16x16x32_bf16 v[56:59], v[164:167], v[188:191], v[56:59]
	v_mfma_f32_16x16x32_bf16 v[44:47], v[148:151], v[196:199], v[44:47]
	v_mfma_f32_16x16x32_bf16 v[40:43], v[164:167], v[196:199], v[40:43]
	v_mfma_f32_16x16x32_bf16 v[28:31], v[148:151], v[204:207], v[28:31]
	v_mfma_f32_16x16x32_bf16 v[24:27], v[164:167], v[204:207], v[24:27]
	v_mfma_f32_16x16x32_bf16 v[12:15], v[148:151], v[212:215], v[12:15]
	v_mfma_f32_16x16x32_bf16 v[8:11], v[164:167], v[212:215], v[8:11]
	s_setprio 0
	s_setprio 1
	v_mfma_f32_16x16x32_bf16 v[52:55], v[168:171], v[184:187], v[52:55]
	v_mfma_f32_16x16x32_bf16 v[48:51], v[176:179], v[184:187], v[48:51]
	v_mfma_f32_16x16x32_bf16 v[36:39], v[168:171], v[192:195], v[36:39]
	v_mfma_f32_16x16x32_bf16 v[32:35], v[176:179], v[192:195], v[32:35]
	v_mfma_f32_16x16x32_bf16 v[20:23], v[168:171], v[200:203], v[20:23]
	v_mfma_f32_16x16x32_bf16 v[16:19], v[176:179], v[200:203], v[16:19]
	v_mfma_f32_16x16x32_bf16 v[4:7], v[168:171], v[208:211], v[4:7]
	v_mfma_f32_16x16x32_bf16 v[0:3], v[176:179], v[208:211], v[0:3]
	v_mfma_f32_16x16x32_bf16 v[52:55], v[172:175], v[188:191], v[52:55]
	v_mfma_f32_16x16x32_bf16 v[48:51], v[180:183], v[188:191], v[48:51]
	v_mfma_f32_16x16x32_bf16 v[36:39], v[172:175], v[196:199], v[36:39]
	v_mfma_f32_16x16x32_bf16 v[32:35], v[180:183], v[196:199], v[32:35]
	v_mfma_f32_16x16x32_bf16 v[20:23], v[172:175], v[204:207], v[20:23]
	v_mfma_f32_16x16x32_bf16 v[16:19], v[180:183], v[204:207], v[16:19]
	v_mfma_f32_16x16x32_bf16 v[4:7], v[172:175], v[212:215], v[4:7]
	v_mfma_f32_16x16x32_bf16 v[0:3], v[180:183], v[212:215], v[0:3]
	s_setprio 0
	s_barrier
; #define PG8_STAGE(bufoff, gbase, voff) do { _Pragma("unroll") for (int _i = 0; _i < 2; ++_i) \
;         __builtin_amdgcn_global_load_lds((const unsigned*)((const char*)(gbase) + (voff)[_i]), (PG8_LAS unsigned*)(lds + (bufoff) + ldsw + _i * 8192), 16, 0, 0); } while (0)
; #define PG8_LDA(dst, b, h) do { _Pragma("unroll") for (int m = 0; m < 4; ++m) _Pragma("unroll") for (int k = 0; k < 2; ++k) dst[m][k] = *(const PG8_LAS bf16x8*)(lds + PG8_SA(b, h) + aoff + m * 2048 + k * 1024); } while (0)
; #define PG8_LDB(dst, b, h) do { _Pragma("unroll") for (int n = 0; n < 2; ++n) _Pragma("unroll") for (int k = 0; k < 2; ++k) dst[n][k] = *(const PG8_LAS bf16x8*)(lds + PG8_SB(b, h) + boff + n * 2048 + k * 1024); } while (0)
; #define PG8_MMA(ai, bj, At, Bt) do { __builtin_amdgcn_s_setprio(1); _Pragma("unroll") for (int m = 0; m < 4; ++m) _Pragma("unroll") for (int n = 0; n < 2; ++n) _Pragma("unroll") for (int k = 0; k < 2; ++k) \
;         acc[ai][bj][m][n] = __builtin_amdgcn_mfma_f32_16x16x32_bf16(Bt[n][k], At[m][k], acc[ai][bj][m][n], 0, 0, 0); __builtin_amdgcn_s_setprio(0); } while (0)
; #define PG8_WAIT_V(n) asm volatile("s_waitcnt vmcnt(" #n ")" ::: "memory")
; #define PG8_WAIT_L(n) asm volatile("s_waitcnt lgkmcnt(" #n ")" ::: "memory")
; #define PG8_BAR __builtin_amdgcn_s_barrier()
; template <class Epi, class Sched, bool ALIGN_EPI = false, bool SP2 = false>
; __device__ __forceinline__ void gemm_phase(PG8_LAS unsigned char* lds, const Gemm g, const Sched& S, const Epi& E, int wv) {
;     ...
;         for (int t = 0; t < nt; t += 2) {
;             const bool last = (t == nt - 2);
;             const char* a1 = cA + (size_t)(t + 1) * kstep;
;             const char* a2 = last ? nA : cA + (size_t)(t + 2) * kstep; const char* b2 = last ? nB : cB + (size_t)(t + 2) * kstep;
;             const char* a3 = a2 + kstep; const char* b3 = b2 + kstep;
;     ...
;             PG8_LDB(B0, 1, 0); PG8_LDB(B1, 1, 1); PG8_SCHED; PG8_LDA(At, 1, 0); PG8_STAGE(PG8_SA(0, 1), a2 + hstepA, voffA);
;             PG8_WAIT_V(8); PG8_WAIT_L(0); PG8_BAR; PG8_MMA(0, 0, At, B0); PG8_MMA(0, 1, At, B1); PG8_BAR; PG8_SCHED;
;             PG8_LDA(At, 1, 1); PG8_STAGE(PG8_SB(1, 0), b3, voffB); PG8_STAGE(PG8_SB(1, 1), b3 + hstepB, voffB); PG8_STAGE(PG8_SA(1, 0), a3, voffA);
;             PG8_WAIT_V(8); PG8_WAIT_L(0); PG8_BAR; PG8_MMA(1, 0, At, B0); PG8_MMA(1, 1, At, B1); PG8_BAR; PG8_SCHED;
	s_add_i32 s72, 0, 0x18000
	v_add_u32_e32 v159, s72, v153
	s_add_i32 s73, 0, 0x1c000
	ds_read_b128 v[144:147], v159
	ds_read_b128 v[148:151], v159 offset:1024
	ds_read_b128 v[160:163], v159 offset:2048
	ds_read_b128 v[164:167], v159 offset:3072
	v_add_u32_e32 v159, s73, v153
	ds_read_b128 v[168:171], v159
	ds_read_b128 v[172:175], v159 offset:1024
	ds_read_b128 v[176:179], v159 offset:2048
	ds_read_b128 v[180:183], v159 offset:3072
	s_add_u32 s0, s46, 0x40000
	s_addc_u32 s1, s47, 0
	s_mov_b32 m0, s54
	ds_read_b128 v[184:187], v157 offset:32768
	ds_read_b128 v[188:191], v157 offset:33792
	ds_read_b128 v[192:195], v157 offset:34816
	ds_read_b128 v[196:199], v157 offset:35840
	ds_read_b128 v[200:203], v157 offset:36864
	ds_read_b128 v[204:207], v157 offset:37888
	ds_read_b128 v[208:211], v157 offset:38912
	ds_read_b128 v[212:215], v157 offset:39936
	global_load_lds_dwordx4 v128, s[0:1]
	s_mov_b32 m0, s55
	s_nop 0
	global_load_lds_dwordx4 v132, s[0:1]
	s_waitcnt vmcnt(8)
	s_waitcnt lgkmcnt(0)
	s_barrier
	s_setprio 1
	s_waitcnt lgkmcnt(0)
	v_mfma_f32_16x16x32_bf16 v[124:127], v[144:147], v[184:187], v[124:127]
	v_mfma_f32_16x16x32_bf16 v[120:123], v[160:163], v[184:187], v[120:123]
	v_mfma_f32_16x16x32_bf16 v[108:111], v[144:147], v[192:195], v[108:111]
	v_mfma_f32_16x16x32_bf16 v[104:107], v[160:163], v[192:195], v[104:107]
	v_mfma_f32_16x16x32_bf16 v[92:95], v[144:147], v[200:203], v[92:95]
	v_mfma_f32_16x16x32_bf16 v[88:91], v[160:163], v[200:203], v[88:91]
	v_mfma_f32_16x16x32_bf16 v[76:79], v[144:147], v[208:211], v[76:79]
	v_mfma_f32_16x16x32_bf16 v[72:75], v[160:163], v[208:211], v[72:75]
	v_mfma_f32_16x16x32_bf16 v[124:127], v[148:151], v[188:191], v[124:127]
	v_mfma_f32_16x16x32_bf16 v[120:123], v[164:167], v[188:191], v[120:123]
	v_mfma_f32_16x16x32_bf16 v[108:111], v[148:151], v[196:199], v[108:111]
	v_mfma_f32_16x16x32_bf16 v[104:107], v[164:167], v[196:199], v[104:107]
	v_mfma_f32_16x16x32_bf16 v[92:95], v[148:151], v[204:207], v[92:95]
	v_mfma_f32_16x16x32_bf16 v[88:91], v[164:167], v[204:207], v[88:91]
	v_mfma_f32_16x16x32_bf16 v[76:79], v[148:151], v[212:215], v[76:79]
	v_mfma_f32_16x16x32_bf16 v[72:75], v[164:167], v[212:215], v[72:75]
	s_setprio 0
	s_setprio 1
	v_mfma_f32_16x16x32_bf16 v[116:119], v[168:171], v[184:187], v[116:119]
	v_mfma_f32_16x16x32_bf16 v[112:115], v[176:179], v[184:187], v[112:115]
	v_mfma_f32_16x16x32_bf16 v[100:103], v[168:171], v[192:195], v[100:103]
	v_mfma_f32_16x16x32_bf16 v[96:99], v[176:179], v[192:195], v[96:99]
	v_mfma_f32_16x16x32_bf16 v[84:87], v[168:171], v[200:203], v[84:87]
	v_mfma_f32_16x16x32_bf16 v[80:83], v[176:179], v[200:203], v[80:83]
	v_mfma_f32_16x16x32_bf16 v[68:71], v[168:171], v[208:211], v[68:71]
	v_mfma_f32_16x16x32_bf16 v[64:67], v[176:179], v[208:211], v[64:67]
	v_mfma_f32_16x16x32_bf16 v[116:119], v[172:175], v[188:191], v[116:119]
	v_mfma_f32_16x16x32_bf16 v[112:115], v[180:183], v[188:191], v[112:115]
	v_mfma_f32_16x16x32_bf16 v[100:103], v[172:175], v[196:199], v[100:103]
	v_mfma_f32_16x16x32_bf16 v[96:99], v[180:183], v[196:199], v[96:99]
	v_mfma_f32_16x16x32_bf16 v[84:87], v[172:175], v[204:207], v[84:87]
	v_mfma_f32_16x16x32_bf16 v[80:83], v[180:183], v[204:207], v[80:83]
	v_mfma_f32_16x16x32_bf16 v[68:71], v[172:175], v[212:215], v[68:71]
	v_mfma_f32_16x16x32_bf16 v[64:67], v[180:183], v[212:215], v[64:67]
	s_setprio 0
	s_barrier
	s_add_i32 s0, s72, s51
	s_add_u32 s76, s44, 0x80
	s_addc_u32 s77, s45, 0
	s_mov_b32 m0, s0
	ds_read_b128 v[184:187], v157 offset:49152
	ds_read_b128 v[188:191], v157 offset:50176
	ds_read_b128 v[192:195], v157 offset:51200
	ds_read_b128 v[196:199], v157 offset:52224
	ds_read_b128 v[200:203], v157 offset:53248
	ds_read_b128 v[204:207], v157 offset:54272
	ds_read_b128 v[208:211], v157 offset:55296
	ds_read_b128 v[212:215], v157 offset:56320
	global_load_lds_dwordx4 v130, s[76:77]
	s_add_i32 m0, s0, 0x2000
	s_add_u32 s0, s44, 0x40080
	s_addc_u32 s1, s45, 0
	s_add_i32 s44, s73, s51
	global_load_lds_dwordx4 v134, s[76:77]
	s_mov_b32 m0, s44
	s_nop 0
	global_load_lds_dwordx4 v130, s[0:1]
	s_add_i32 m0, s44, 0x2000
	s_nop 0
	global_load_lds_dwordx4 v134, s[0:1]
	s_add_u32 s78, s46, 0x80
	s_addc_u32 s79, s47, 0
	s_mov_b32 m0, s57
	s_nop 0
	global_load_lds_dwordx4 v128, s[78:79]
	s_mov_b32 m0, s58
	s_nop 0
	global_load_lds_dwordx4 v132, s[78:79]
	s_waitcnt vmcnt(8)
	s_waitcnt lgkmcnt(0)
	s_barrier
	s_setprio 1
	s_waitcnt lgkmcnt(0)
	v_mfma_f32_16x16x32_bf16 v[60:63], v[144:147], v[184:187], v[60:63]
	v_mfma_f32_16x16x32_bf16 v[56:59], v[160:163], v[184:187], v[56:59]
	v_mfma_f32_16x16x32_bf16 v[44:47], v[144:147], v[192:195], v[44:47]
	v_mfma_f32_16x16x32_bf16 v[40:43], v[160:163], v[192:195], v[40:43]
	v_mfma_f32_16x16x32_bf16 v[28:31], v[144:147], v[200:203], v[28:31]
	v_mfma_f32_16x16x32_bf16 v[24:27], v[160:163], v[200:203], v[24:27]
	v_mfma_f32_16x16x32_bf16 v[12:15], v[144:147], v[208:211], v[12:15]
	v_mfma_f32_16x16x32_bf16 v[8:11], v[160:163], v[208:211], v[8:11]
	v_mfma_f32_16x16x32_bf16 v[60:63], v[148:151], v[188:191], v[60:63]
	v_mfma_f32_16x16x32_bf16 v[56:59], v[164:167], v[188:191], v[56:59]
	v_mfma_f32_16x16x32_bf16 v[44:47], v[148:151], v[196:199], v[44:47]
	v_mfma_f32_16x16x32_bf16 v[40:43], v[164:167], v[196:199], v[40:43]
	v_mfma_f32_16x16x32_bf16 v[28:31], v[148:151], v[204:207], v[28:31]
	v_mfma_f32_16x16x32_bf16 v[24:27], v[164:167], v[204:207], v[24:27]
	v_mfma_f32_16x16x32_bf16 v[12:15], v[148:151], v[212:215], v[12:15]
	v_mfma_f32_16x16x32_bf16 v[8:11], v[164:167], v[212:215], v[8:11]
	s_setprio 0
	s_setprio 1
	v_mfma_f32_16x16x32_bf16 v[52:55], v[168:171], v[184:187], v[52:55]
	v_mfma_f32_16x16x32_bf16 v[48:51], v[176:179], v[184:187], v[48:51]
	v_mfma_f32_16x16x32_bf16 v[36:39], v[168:171], v[192:195], v[36:39]
	v_mfma_f32_16x16x32_bf16 v[32:35], v[176:179], v[192:195], v[32:35]
	v_mfma_f32_16x16x32_bf16 v[20:23], v[168:171], v[200:203], v[20:23]
	v_mfma_f32_16x16x32_bf16 v[16:19], v[176:179], v[200:203], v[16:19]
	v_mfma_f32_16x16x32_bf16 v[4:7], v[168:171], v[208:211], v[4:7]
	v_mfma_f32_16x16x32_bf16 v[0:3], v[176:179], v[208:211], v[0:3]
	v_mfma_f32_16x16x32_bf16 v[52:55], v[172:175], v[188:191], v[52:55]
	v_mfma_f32_16x16x32_bf16 v[48:51], v[180:183], v[188:191], v[48:51]
	v_mfma_f32_16x16x32_bf16 v[36:39], v[172:175], v[196:199], v[36:39]
	v_mfma_f32_16x16x32_bf16 v[32:35], v[180:183], v[196:199], v[32:35]
	v_mfma_f32_16x16x32_bf16 v[20:23], v[172:175], v[204:207], v[20:23]
	v_mfma_f32_16x16x32_bf16 v[16:19], v[180:183], v[204:207], v[16:19]
	v_mfma_f32_16x16x32_bf16 v[4:7], v[172:175], v[212:215], v[4:7]
	v_mfma_f32_16x16x32_bf16 v[0:3], v[180:183], v[212:215], v[0:3]
	s_setprio 0
	s_barrier
	s_add_i32 s71, s71, 2
	s_add_u32 s42, s42, 0x100
	s_addc_u32 s43, s43, 0
	s_add_u32 s69, s69, 0x100
	s_addc_u32 s70, s70, 0
	s_cmp_gt_u32 s71, 13
	s_cbranch_scc0 .LBB0_2067
	s_and_b64 vcc, exec, s[18:19]
	s_cbranch_vccz .LBB0_2070
	s_barrier

; #define PG8_STAGE(bufoff, gbase, voff) do { _Pragma("unroll") for (int _i = 0; _i < 2; ++_i) \
;         __builtin_amdgcn_global_load_lds((const unsigned*)((const char*)(gbase) + (voff)[_i]), (PG8_LAS unsigned*)(lds + (bufoff) + ldsw + _i * 8192), 16, 0, 0); } while (0)
; #define PG8_LDA(dst, b, h) do { _Pragma("unroll") for (int m = 0; m < 4; ++m) _Pragma("unroll") for (int k = 0; k < 2; ++k) dst[m][k] = *(const PG8_LAS bf16x8*)(lds + PG8_SA(b, h) + aoff + m * 2048 + k * 1024); } while (0)
; #define PG8_LDB(dst, b, h) do { _Pragma("unroll") for (int n = 0; n < 2; ++n) _Pragma("unroll") for (int k = 0; k < 2; ++k) dst[n][k] = *(const PG8_LAS bf16x8*)(lds + PG8_SB(b, h) + boff + n * 2048 + k * 1024); } while (0)
; #define PG8_MMA(ai, bj, At, Bt) do { __builtin_amdgcn_s_setprio(1); _Pragma("unroll") for (int m = 0; m < 4; ++m) _Pragma("unroll") for (int n = 0; n < 2; ++n) _Pragma("unroll") for (int k = 0; k < 2; ++k) \
;         acc[ai][bj][m][n] = __builtin_amdgcn_mfma_f32_16x16x32_bf16(Bt[n][k], At[m][k], acc[ai][bj][m][n], 0, 0, 0); __builtin_amdgcn_s_setprio(0); } while (0)
; #define PG8_WAIT_V(n) asm volatile("s_waitcnt vmcnt(" #n ")" ::: "memory")
; #define PG8_WAIT_L(n) asm volatile("s_waitcnt lgkmcnt(" #n ")" ::: "memory")
; #define PG8_BAR __builtin_amdgcn_s_barrier()
; #define PG8_SCHED __builtin_amdgcn_sched_barrier(0)
; template <class Epi, class Sched, bool ALIGN_EPI = false, bool SP2 = false>
; __device__ __forceinline__ void gemm_phase(PG8_LAS unsigned char* lds, const Gemm g, const Sched& S, const Epi& E, int wv) {
;     ...
;             PG8_LDB(B0, 0, 0); PG8_LDB(B1, 0, 1); PG8_SCHED; PG8_LDA(At, 0, 0); PG8_STAGE(PG8_SA(1, 1), a1 + hstepA, voffA);
;             PG8_WAIT_V(8); PG8_WAIT_L(0); PG8_BAR; PG8_MMA(0, 0, At, B0); PG8_MMA(0, 1, At, B1); PG8_BAR; PG8_SCHED;
;             PG8_LDA(At, 0, 1); PG8_STAGE(PG8_SB(0, 0), b2, voffB); PG8_STAGE(PG8_SB(0, 1), b2 + hstepB, voffB); PG8_STAGE(PG8_SA(0, 0), a2, voffA);
;             PG8_WAIT_V(8); PG8_WAIT_L(0); PG8_BAR; PG8_MMA(1, 0, At, B0); PG8_MMA(1, 1, At, B1); PG8_BAR; PG8_SCHED;
.LBB0_2102:
	ds_read_b128 v[144:147], v153
	ds_read_b128 v[156:159], v153 offset:1024
	ds_read_b128 v[160:163], v153 offset:2048
	ds_read_b128 v[164:167], v153 offset:3072
	ds_read_b128 v[168:171], v154
	ds_read_b128 v[172:175], v154 offset:1024
	ds_read_b128 v[176:179], v154 offset:2048
	ds_read_b128 v[180:183], v154 offset:3072
	s_add_u32 s38, s36, 0xfff00080
	s_addc_u32 s39, s37, -1
	s_cmp_eq_u32 s59, 60
	s_cselect_b32 s41, s23, s39
	s_cselect_b32 s40, s55, s38
	s_cselect_b32 s39, s21, s58
	s_cselect_b32 s38, s56, s57
	s_add_i32 m0, s29, 0xc000
	ds_read_b128 v[184:187], v155
	ds_read_b128 v[188:191], v155 offset:1024
	ds_read_b128 v[192:195], v155 offset:2048
	ds_read_b128 v[196:199], v155 offset:3072
	ds_read_b128 v[200:203], v155 offset:4096
	ds_read_b128 v[204:207], v155 offset:5120
	ds_read_b128 v[208:211], v155 offset:6144
	ds_read_b128 v[212:215], v155 offset:7168
	global_load_lds_dwordx4 v136, s[36:37]
	s_add_i32 m0, s29, 0xe000
	s_nop 0
	global_load_lds_dwordx4 v138, s[36:37]
	s_waitcnt vmcnt(8)
	s_waitcnt lgkmcnt(0)
	s_barrier
	s_setprio 1
	s_waitcnt lgkmcnt(0)
	v_mfma_f32_16x16x32_bf16 v[124:127], v[144:147], v[184:187], v[124:127]
	v_mfma_f32_16x16x32_bf16 v[120:123], v[160:163], v[184:187], v[120:123]
	v_mfma_f32_16x16x32_bf16 v[108:111], v[144:147], v[192:195], v[108:111]
	v_mfma_f32_16x16x32_bf16 v[104:107], v[160:163], v[192:195], v[104:107]
	v_mfma_f32_16x16x32_bf16 v[92:95], v[144:147], v[200:203], v[92:95]
	v_mfma_f32_16x16x32_bf16 v[88:91], v[160:163], v[200:203], v[88:91]
	v_mfma_f32_16x16x32_bf16 v[76:79], v[144:147], v[208:211], v[76:79]
	v_mfma_f32_16x16x32_bf16 v[72:75], v[160:163], v[208:211], v[72:75]
	v_mfma_f32_16x16x32_bf16 v[124:127], v[156:159], v[188:191], v[124:127]
	v_mfma_f32_16x16x32_bf16 v[120:123], v[164:167], v[188:191], v[120:123]
	v_mfma_f32_16x16x32_bf16 v[108:111], v[156:159], v[196:199], v[108:111]
	v_mfma_f32_16x16x32_bf16 v[104:107], v[164:167], v[196:199], v[104:107]
	v_mfma_f32_16x16x32_bf16 v[92:95], v[156:159], v[204:207], v[92:95]
	v_mfma_f32_16x16x32_bf16 v[88:91], v[164:167], v[204:207], v[88:91]
	v_mfma_f32_16x16x32_bf16 v[76:79], v[156:159], v[212:215], v[76:79]
	v_mfma_f32_16x16x32_bf16 v[72:75], v[164:167], v[212:215], v[72:75]
	s_setprio 0
	s_setprio 1
	v_mfma_f32_16x16x32_bf16 v[116:119], v[168:171], v[184:187], v[116:119]
	v_mfma_f32_16x16x32_bf16 v[112:115], v[176:179], v[184:187], v[112:115]
	v_mfma_f32_16x16x32_bf16 v[100:103], v[168:171], v[192:195], v[100:103]
	v_mfma_f32_16x16x32_bf16 v[96:99], v[176:179], v[192:195], v[96:99]
	v_mfma_f32_16x16x32_bf16 v[84:87], v[168:171], v[200:203], v[84:87]
	v_mfma_f32_16x16x32_bf16 v[80:83], v[176:179], v[200:203], v[80:83]
	v_mfma_f32_16x16x32_bf16 v[68:71], v[168:171], v[208:211], v[68:71]
	v_mfma_f32_16x16x32_bf16 v[64:67], v[176:179], v[208:211], v[64:67]
	v_mfma_f32_16x16x32_bf16 v[116:119], v[172:175], v[188:191], v[116:119]
	v_mfma_f32_16x16x32_bf16 v[112:115], v[180:183], v[188:191], v[112:115]
	v_mfma_f32_16x16x32_bf16 v[100:103], v[172:175], v[196:199], v[100:103]
	v_mfma_f32_16x16x32_bf16 v[96:99], v[180:183], v[196:199], v[96:99]
	v_mfma_f32_16x16x32_bf16 v[84:87], v[172:175], v[204:207], v[84:87]
	v_mfma_f32_16x16x32_bf16 v[80:83], v[180:183], v[204:207], v[80:83]
	v_mfma_f32_16x16x32_bf16 v[68:71], v[172:175], v[212:215], v[68:71]
	v_mfma_f32_16x16x32_bf16 v[64:67], v[180:183], v[212:215], v[64:67]
	s_setprio 0
	s_barrier
	s_add_i32 s60, s52, s44
	s_mov_b32 m0, s60
	ds_read_b128 v[184:187], v155 offset:16384
	ds_read_b128 v[188:191], v155 offset:17408
	ds_read_b128 v[192:195], v155 offset:18432
	ds_read_b128 v[196:199], v155 offset:19456
	ds_read_b128 v[200:203], v155 offset:20480
	ds_read_b128 v[204:207], v155 offset:21504
	ds_read_b128 v[208:211], v155 offset:22528
	ds_read_b128 v[212:215], v155 offset:23552
	global_load_lds_dwordx4 v130, s[38:39]
	s_add_i32 m0, s60, 0x2000
	s_add_u32 s60, s38, 0x100000
	s_addc_u32 s61, s39, 0
	s_add_i32 s62, s53, s44
	global_load_lds_dwordx4 v134, s[38:39]
	s_mov_b32 m0, s62
	s_add_u32 s82, s40, 0x80
	s_addc_u32 s83, s41, 0
	global_load_lds_dwordx4 v130, s[60:61]
	s_add_i32 m0, s62, 0x2000
	s_nop 0
	global_load_lds_dwordx4 v134, s[60:61]
	s_mov_b32 m0, s29
	s_nop 0
	global_load_lds_dwordx4 v128, s[40:41]
	s_mov_b32 m0, s45
	s_nop 0
	global_load_lds_dwordx4 v132, s[40:41]
	s_waitcnt vmcnt(8)
	s_waitcnt lgkmcnt(0)
	s_barrier
	s_setprio 1
	s_waitcnt lgkmcnt(0)
	v_mfma_f32_16x16x32_bf16 v[60:63], v[144:147], v[184:187], v[60:63]
	v_mfma_f32_16x16x32_bf16 v[56:59], v[160:163], v[184:187], v[56:59]
	v_mfma_f32_16x16x32_bf16 v[44:47], v[144:147], v[192:195], v[44:47]
	v_mfma_f32_16x16x32_bf16 v[40:43], v[160:163], v[192:195], v[40:43]
	v_mfma_f32_16x16x32_bf16 v[28:31], v[144:147], v[200:203], v[28:31]
	v_mfma_f32_16x16x32_bf16 v[24:27], v[160:163], v[200:203], v[24:27]
	v_mfma_f32_16x16x32_bf16 v[12:15], v[144:147], v[208:211], v[12:15]
	v_mfma_f32_16x16x32_bf16 v[8:11], v[160:163], v[208:211], v[8:11]
	v_mfma_f32_16x16x32_bf16 v[60:63], v[156:159], v[188:191], v[60:63]
	v_mfma_f32_16x16x32_bf16 v[56:59], v[164:167], v[188:191], v[56:59]
	v_mfma_f32_16x16x32_bf16 v[44:47], v[156:159], v[196:199], v[44:47]
	v_mfma_f32_16x16x32_bf16 v[40:43], v[164:167], v[196:199], v[40:43]
	v_mfma_f32_16x16x32_bf16 v[28:31], v[156:159], v[204:207], v[28:31]
	v_mfma_f32_16x16x32_bf16 v[24:27], v[164:167], v[204:207], v[24:27]
	v_mfma_f32_16x16x32_bf16 v[12:15], v[156:159], v[212:215], v[12:15]
	v_mfma_f32_16x16x32_bf16 v[8:11], v[164:167], v[212:215], v[8:11]
	s_setprio 0
	s_setprio 1
	v_mfma_f32_16x16x32_bf16 v[52:55], v[168:171], v[184:187], v[52:55]
	v_mfma_f32_16x16x32_bf16 v[48:51], v[176:179], v[184:187], v[48:51]
	v_mfma_f32_16x16x32_bf16 v[36:39], v[168:171], v[192:195], v[36:39]
	v_mfma_f32_16x16x32_bf16 v[32:35], v[176:179], v[192:195], v[32:35]
	v_mfma_f32_16x16x32_bf16 v[20:23], v[168:171], v[200:203], v[20:23]
	v_mfma_f32_16x16x32_bf16 v[16:19], v[176:179], v[200:203], v[16:19]
	v_mfma_f32_16x16x32_bf16 v[4:7], v[168:171], v[208:211], v[4:7]
	v_mfma_f32_16x16x32_bf16 v[0:3], v[176:179], v[208:211], v[0:3]
	v_mfma_f32_16x16x32_bf16 v[52:55], v[172:175], v[188:191], v[52:55]
	v_mfma_f32_16x16x32_bf16 v[48:51], v[180:183], v[188:191], v[48:51]
	v_mfma_f32_16x16x32_bf16 v[36:39], v[172:175], v[196:199], v[36:39]
	v_mfma_f32_16x16x32_bf16 v[32:35], v[180:183], v[196:199], v[32:35]
	v_mfma_f32_16x16x32_bf16 v[20:23], v[172:175], v[204:207], v[20:23]
	v_mfma_f32_16x16x32_bf16 v[16:19], v[180:183], v[204:207], v[16:19]
	v_mfma_f32_16x16x32_bf16 v[4:7], v[172:175], v[212:215], v[4:7]
	v_mfma_f32_16x16x32_bf16 v[0:3], v[180:183], v[212:215], v[0:3]
	s_setprio 0
	s_barrier
; #define PG8_STAGE(bufoff, gbase, voff) do { _Pragma("unroll") for (int _i = 0; _i < 2; ++_i) \
;         __builtin_amdgcn_global_load_lds((const unsigned*)((const char*)(gbase) + (voff)[_i]), (PG8_LAS unsigned*)(lds + (bufoff) + ldsw + _i * 8192), 16, 0, 0); } while (0)
; #define PG8_LDA(dst, b, h) do { _Pragma("unroll") for (int m = 0; m < 4; ++m) _Pragma("unroll") for (int k = 0; k < 2; ++k) dst[m][k] = *(const PG8_LAS bf16x8*)(lds + PG8_SA(b, h) + aoff + m * 2048 + k * 1024); } while (0)
; #define PG8_LDB(dst, b, h) do { _Pragma("unroll") for (int n = 0; n < 2; ++n) _Pragma("unroll") for (int k = 0; k < 2; ++k) dst[n][k] = *(const PG8_LAS bf16x8*)(lds + PG8_SB(b, h) + boff + n * 2048 + k * 1024); } while (0)
; #define PG8_MMA(ai, bj, At, Bt) do { __builtin_amdgcn_s_setprio(1); _Pragma("unroll") for (int m = 0; m < 4; ++m) _Pragma("unroll") for (int n = 0; n < 2; ++n) _Pragma("unroll") for (int k = 0; k < 2; ++k) \
;         acc[ai][bj][m][n] = __builtin_amdgcn_mfma_f32_16x16x32_bf16(Bt[n][k], At[m][k], acc[ai][bj][m][n], 0, 0, 0); __builtin_amdgcn_s_setprio(0); } while (0)
; #define PG8_WAIT_V(n) asm volatile("s_waitcnt vmcnt(" #n ")" ::: "memory")
; #define PG8_WAIT_L(n) asm volatile("s_waitcnt lgkmcnt(" #n ")" ::: "memory")
; #define PG8_BAR __builtin_amdgcn_s_barrier()
; template <class Epi, class Sched, bool ALIGN_EPI = false, bool SP2 = false>
; __device__ __forceinline__ void gemm_phase(PG8_LAS unsigned char* lds, const Gemm g, const Sched& S, const Epi& E, int wv) {
;     ...
;         for (int t = 0; t < nt; t += 2) {
;             const bool last = (t == nt - 2);
;             const char* a1 = cA + (size_t)(t + 1) * kstep;
;             const char* a2 = last ? nA : cA + (size_t)(t + 2) * kstep; const char* b2 = last ? nB : cB + (size_t)(t + 2) * kstep;
;             const char* a3 = a2 + kstep; const char* b3 = b2 + kstep;
;     ...
;             PG8_LDB(B0, 1, 0); PG8_LDB(B1, 1, 1); PG8_SCHED; PG8_LDA(At, 1, 0); PG8_STAGE(PG8_SA(0, 1), a2 + hstepA, voffA);
;             PG8_WAIT_V(8); PG8_WAIT_L(0); PG8_BAR; PG8_MMA(0, 0, At, B0); PG8_MMA(0, 1, At, B1); PG8_BAR; PG8_SCHED;
;             PG8_LDA(At, 1, 1); PG8_STAGE(PG8_SB(1, 0), b3, voffB); PG8_STAGE(PG8_SB(1, 1), b3 + hstepB, voffB); PG8_STAGE(PG8_SA(1, 0), a3, voffA);
;             PG8_WAIT_V(8); PG8_WAIT_L(0); PG8_BAR; PG8_MMA(1, 0, At, B0); PG8_MMA(1, 1, At, B1); PG8_BAR; PG8_SCHED;
	s_add_i32 s60, 0, 0x18000
	s_add_i32 s61, 0, 0x1c000
	v_add_u32_e32 v164, s60, v151
	v_add_u32_e32 v180, s61, v151
	ds_read_b128 v[144:147], v164
	ds_read_b128 v[156:159], v164 offset:1024
	ds_read_b128 v[160:163], v164 offset:2048
	ds_read_b128 v[164:167], v164 offset:3072
	ds_read_b128 v[168:171], v180
	ds_read_b128 v[172:175], v180 offset:1024
	ds_read_b128 v[176:179], v180 offset:2048
	ds_read_b128 v[180:183], v180 offset:3072
	s_add_u32 s40, s40, 0x100000
	s_addc_u32 s41, s41, 0
	s_mov_b32 m0, s46
	ds_read_b128 v[184:187], v155 offset:32768
	ds_read_b128 v[188:191], v155 offset:33792
	ds_read_b128 v[192:195], v155 offset:34816
	ds_read_b128 v[196:199], v155 offset:35840
	ds_read_b128 v[200:203], v155 offset:36864
	ds_read_b128 v[204:207], v155 offset:37888
	ds_read_b128 v[208:211], v155 offset:38912
	ds_read_b128 v[212:215], v155 offset:39936
	global_load_lds_dwordx4 v128, s[40:41]
	s_mov_b32 m0, s47
	s_nop 0
	global_load_lds_dwordx4 v132, s[40:41]
	s_waitcnt vmcnt(8)
	s_waitcnt lgkmcnt(0)
	s_barrier
	s_setprio 1
	s_waitcnt lgkmcnt(0)
	v_mfma_f32_16x16x32_bf16 v[124:127], v[144:147], v[184:187], v[124:127]
	v_mfma_f32_16x16x32_bf16 v[120:123], v[160:163], v[184:187], v[120:123]
	v_mfma_f32_16x16x32_bf16 v[108:111], v[144:147], v[192:195], v[108:111]
	v_mfma_f32_16x16x32_bf16 v[104:107], v[160:163], v[192:195], v[104:107]
	v_mfma_f32_16x16x32_bf16 v[92:95], v[144:147], v[200:203], v[92:95]
	v_mfma_f32_16x16x32_bf16 v[88:91], v[160:163], v[200:203], v[88:91]
	v_mfma_f32_16x16x32_bf16 v[76:79], v[144:147], v[208:211], v[76:79]
	v_mfma_f32_16x16x32_bf16 v[72:75], v[160:163], v[208:211], v[72:75]
	v_mfma_f32_16x16x32_bf16 v[124:127], v[156:159], v[188:191], v[124:127]
	v_mfma_f32_16x16x32_bf16 v[120:123], v[164:167], v[188:191], v[120:123]
	v_mfma_f32_16x16x32_bf16 v[108:111], v[156:159], v[196:199], v[108:111]
	v_mfma_f32_16x16x32_bf16 v[104:107], v[164:167], v[196:199], v[104:107]
	v_mfma_f32_16x16x32_bf16 v[92:95], v[156:159], v[204:207], v[92:95]
	v_mfma_f32_16x16x32_bf16 v[88:91], v[164:167], v[204:207], v[88:91]
	v_mfma_f32_16x16x32_bf16 v[76:79], v[156:159], v[212:215], v[76:79]
	v_mfma_f32_16x16x32_bf16 v[72:75], v[164:167], v[212:215], v[72:75]
	s_setprio 0
	s_setprio 1
	v_mfma_f32_16x16x32_bf16 v[116:119], v[168:171], v[184:187], v[116:119]
	v_mfma_f32_16x16x32_bf16 v[112:115], v[176:179], v[184:187], v[112:115]
	v_mfma_f32_16x16x32_bf16 v[100:103], v[168:171], v[192:195], v[100:103]
	v_mfma_f32_16x16x32_bf16 v[96:99], v[176:179], v[192:195], v[96:99]
	v_mfma_f32_16x16x32_bf16 v[84:87], v[168:171], v[200:203], v[84:87]
	v_mfma_f32_16x16x32_bf16 v[80:83], v[176:179], v[200:203], v[80:83]
	v_mfma_f32_16x16x32_bf16 v[68:71], v[168:171], v[208:211], v[68:71]
	v_mfma_f32_16x16x32_bf16 v[64:67], v[176:179], v[208:211], v[64:67]
	v_mfma_f32_16x16x32_bf16 v[116:119], v[172:175], v[188:191], v[116:119]
	v_mfma_f32_16x16x32_bf16 v[112:115], v[180:183], v[188:191], v[112:115]
	v_mfma_f32_16x16x32_bf16 v[100:103], v[172:175], v[196:199], v[100:103]
	v_mfma_f32_16x16x32_bf16 v[96:99], v[180:183], v[196:199], v[96:99]
	v_mfma_f32_16x16x32_bf16 v[84:87], v[172:175], v[204:207], v[84:87]
	v_mfma_f32_16x16x32_bf16 v[80:83], v[180:183], v[204:207], v[80:83]
	v_mfma_f32_16x16x32_bf16 v[68:71], v[172:175], v[212:215], v[68:71]
	v_mfma_f32_16x16x32_bf16 v[64:67], v[180:183], v[212:215], v[64:67]
	s_setprio 0
	s_barrier
	s_add_i32 s40, s60, s44
	s_add_u32 s80, s38, 0x80
	s_addc_u32 s81, s39, 0
	s_mov_b32 m0, s40
	ds_read_b128 v[184:187], v155 offset:49152
	ds_read_b128 v[188:191], v155 offset:50176
	ds_read_b128 v[192:195], v155 offset:51200
	ds_read_b128 v[196:199], v155 offset:52224
	ds_read_b128 v[200:203], v155 offset:53248
	ds_read_b128 v[204:207], v155 offset:54272
	ds_read_b128 v[208:211], v155 offset:55296
	ds_read_b128 v[212:215], v155 offset:56320
	global_load_lds_dwordx4 v130, s[80:81]
	s_add_i32 m0, s40, 0x2000
	s_add_u32 s38, s38, 0x100080
	s_addc_u32 s39, s39, 0
	s_add_i32 s40, s61, s44
	global_load_lds_dwordx4 v134, s[80:81]
	s_mov_b32 m0, s40
	s_nop 0
	global_load_lds_dwordx4 v130, s[38:39]
	s_add_i32 m0, s40, 0x2000
	s_nop 0
	global_load_lds_dwordx4 v134, s[38:39]
	s_mov_b32 m0, s49
	s_nop 0
	global_load_lds_dwordx4 v128, s[82:83]
	s_mov_b32 m0, s50
	s_nop 0
	global_load_lds_dwordx4 v132, s[82:83]
	s_waitcnt vmcnt(8)
	s_waitcnt lgkmcnt(0)
	s_barrier
	s_setprio 1
	s_waitcnt lgkmcnt(0)
	v_mfma_f32_16x16x32_bf16 v[60:63], v[144:147], v[184:187], v[60:63]
	v_mfma_f32_16x16x32_bf16 v[56:59], v[160:163], v[184:187], v[56:59]
	v_mfma_f32_16x16x32_bf16 v[44:47], v[144:147], v[192:195], v[44:47]
	v_mfma_f32_16x16x32_bf16 v[40:43], v[160:163], v[192:195], v[40:43]
	v_mfma_f32_16x16x32_bf16 v[28:31], v[144:147], v[200:203], v[28:31]
	v_mfma_f32_16x16x32_bf16 v[24:27], v[160:163], v[200:203], v[24:27]
	v_mfma_f32_16x16x32_bf16 v[12:15], v[144:147], v[208:211], v[12:15]
	v_mfma_f32_16x16x32_bf16 v[8:11], v[160:163], v[208:211], v[8:11]
	v_mfma_f32_16x16x32_bf16 v[60:63], v[156:159], v[188:191], v[60:63]
	v_mfma_f32_16x16x32_bf16 v[56:59], v[164:167], v[188:191], v[56:59]
	v_mfma_f32_16x16x32_bf16 v[44:47], v[156:159], v[196:199], v[44:47]
	v_mfma_f32_16x16x32_bf16 v[40:43], v[164:167], v[196:199], v[40:43]
	v_mfma_f32_16x16x32_bf16 v[28:31], v[156:159], v[204:207], v[28:31]
	v_mfma_f32_16x16x32_bf16 v[24:27], v[164:167], v[204:207], v[24:27]
	v_mfma_f32_16x16x32_bf16 v[12:15], v[156:159], v[212:215], v[12:15]
	v_mfma_f32_16x16x32_bf16 v[8:11], v[164:167], v[212:215], v[8:11]
	s_setprio 0
	s_setprio 1
	v_mfma_f32_16x16x32_bf16 v[52:55], v[168:171], v[184:187], v[52:55]
	v_mfma_f32_16x16x32_bf16 v[48:51], v[176:179], v[184:187], v[48:51]
	v_mfma_f32_16x16x32_bf16 v[36:39], v[168:171], v[192:195], v[36:39]
	v_mfma_f32_16x16x32_bf16 v[32:35], v[176:179], v[192:195], v[32:35]
	v_mfma_f32_16x16x32_bf16 v[20:23], v[168:171], v[200:203], v[20:23]
	v_mfma_f32_16x16x32_bf16 v[16:19], v[176:179], v[200:203], v[16:19]
	v_mfma_f32_16x16x32_bf16 v[4:7], v[168:171], v[208:211], v[4:7]
	v_mfma_f32_16x16x32_bf16 v[0:3], v[176:179], v[208:211], v[0:3]
	v_mfma_f32_16x16x32_bf16 v[52:55], v[172:175], v[188:191], v[52:55]
	v_mfma_f32_16x16x32_bf16 v[48:51], v[180:183], v[188:191], v[48:51]
	v_mfma_f32_16x16x32_bf16 v[36:39], v[172:175], v[196:199], v[36:39]
	v_mfma_f32_16x16x32_bf16 v[32:35], v[180:183], v[196:199], v[32:35]
	v_mfma_f32_16x16x32_bf16 v[20:23], v[172:175], v[204:207], v[20:23]
	v_mfma_f32_16x16x32_bf16 v[16:19], v[180:183], v[204:207], v[16:19]
	v_mfma_f32_16x16x32_bf16 v[4:7], v[172:175], v[212:215], v[4:7]
	v_mfma_f32_16x16x32_bf16 v[0:3], v[180:183], v[212:215], v[0:3]
	s_setprio 0
	s_barrier
	s_add_i32 s59, s59, 2
	s_add_u32 s36, s36, 0x100
	s_addc_u32 s37, s37, 0
	s_add_u32 s57, s57, 0x100
	s_addc_u32 s58, s58, 0
	s_cmp_gt_u32 s59, 61
	s_cbranch_scc0 .LBB0_2102
	s_and_b64 vcc, exec, s[6:7]
	s_cbranch_vccz .LBB0_2105
	s_barrier

; __global__ void __launch_bounds__(512) fwd_kernel(Params p) {
	.amdhsa_kernel _Z10fwd_kernel6Params
		.amdhsa_group_segment_fixed_size 0
		.amdhsa_private_segment_fixed_size 0
		.amdhsa_kernarg_size 440
		.amdhsa_user_sgpr_count 2
		.amdhsa_user_sgpr_dispatch_ptr 0
		.amdhsa_user_sgpr_queue_ptr 0
		.amdhsa_user_sgpr_kernarg_segment_ptr 1
		.amdhsa_user_sgpr_dispatch_id 0
		.amdhsa_user_sgpr_kernarg_preload_length 0
		.amdhsa_user_sgpr_kernarg_preload_offset 0
		.amdhsa_user_sgpr_private_segment_size 0
		.amdhsa_uses_dynamic_stack 0
		.amdhsa_enable_private_segment 0
		.amdhsa_system_sgpr_workgroup_id_x 1
		.amdhsa_system_sgpr_workgroup_id_y 0
		.amdhsa_system_sgpr_workgroup_id_z 0
		.amdhsa_system_sgpr_workgroup_info 0
		.amdhsa_system_vgpr_workitem_id 2
		.amdhsa_next_free_vgpr 256
		.amdhsa_next_free_sgpr 102
		.amdhsa_accum_offset 256
		.amdhsa_reserve_vcc 1
		.amdhsa_float_round_mode_32 0
		.amdhsa_float_round_mode_16_64 0
		.amdhsa_float_denorm_mode_32 3
		.amdhsa_float_denorm_mode_16_64 3
		.amdhsa_dx10_clamp 1
		.amdhsa_ieee_mode 1
		.amdhsa_fp16_overflow 0
		.amdhsa_tg_split 0
		.amdhsa_exception_fp_ieee_invalid_op 0
		.amdhsa_exception_fp_denorm_src 0
		.amdhsa_exception_fp_ieee_div_zero 0
		.amdhsa_exception_fp_ieee_overflow 0
		.amdhsa_exception_fp_ieee_underflow 0
		.amdhsa_exception_fp_ieee_inexact 0
		.amdhsa_exception_int_div_zero 0
	.end_amdhsa_kernel

; __global__ void __launch_bounds__(512) fwd_kernel(Params p) {
amdhsa.kernels:
  - .agpr_count:     0
    .args:
      - .offset:         0
        .size:           184
        .value_kind:     by_value
      - .offset:         184
        .size:           4
        .value_kind:     hidden_block_count_x
      - .offset:         188
        .size:           4
        .value_kind:     hidden_block_count_y
      - .offset:         192
        .size:           4
        .value_kind:     hidden_block_count_z
      - .offset:         196
        .size:           2
        .value_kind:     hidden_group_size_x
      - .offset:         198
        .size:           2
        .value_kind:     hidden_group_size_y
      - .offset:         200
        .size:           2
        .value_kind:     hidden_group_size_z
      - .offset:         202
        .size:           2
        .value_kind:     hidden_remainder_x
      - .offset:         204
        .size:           2
        .value_kind:     hidden_remainder_y
      - .offset:         206
        .size:           2
        .value_kind:     hidden_remainder_z
      - .offset:         224
        .size:           8
        .value_kind:     hidden_global_offset_x
      - .offset:         232
        .size:           8
        .value_kind:     hidden_global_offset_y
      - .offset:         240
        .size:           8
        .value_kind:     hidden_global_offset_z
      - .offset:         248
        .size:           2
        .value_kind:     hidden_grid_dims
      - .offset:         272
        .size:           8
        .value_kind:     hidden_multigrid_sync_arg
      - .offset:         304
        .size:           4
        .value_kind:     hidden_dynamic_lds_size
    .group_segment_fixed_size: 0
    .kernarg_segment_align: 8
    .kernarg_segment_size: 440
    .language:       OpenCL C
    .language_version:
      - 2
      - 0
    .max_flat_workgroup_size: 512
    .name:           _Z10fwd_kernel6Params
    .private_segment_fixed_size: 0
    .sgpr_count:     108
    .sgpr_spill_count: 9
    .symbol:         _Z10fwd_kernel6Params.kd
    .uniform_work_group_size: 1
    .uses_dynamic_stack: false
    .vgpr_count:     256
    .vgpr_spill_count: 0
    .wavefront_size: 64
